# GEMM MFMA segments: redundant lgkmcnt(0) after the barrier and the mid-segment priority flip pair removed
# baseline (speedup 1.0000x reference)
; #define PG8_STAGE(bufoff, gbase, voff) do { _Pragma("unroll") for (int _i = 0; _i < 2; ++_i) \
;         __builtin_amdgcn_global_load_lds((const unsigned*)((const char*)(gbase) + (voff)[_i]), (LAS unsigned*)(lds + (bufoff) + ldsw + _i * 8192), 16, 0, 0); } while (0)
; #define PG8_LDA(dst, b, h) do { _Pragma("unroll") for (int m = 0; m < 4; ++m) _Pragma("unroll") for (int k = 0; k < 2; ++k) dst[m][k] = *(const LAS bf16x8*)(lds + PG8_SA(b, h) + aoff + m * 2048 + k * 1024); } while (0)
; #define PG8_LDB(dst, b, h) do { _Pragma("unroll") for (int n = 0; n < 2; ++n) _Pragma("unroll") for (int k = 0; k < 2; ++k) dst[n][k] = *(const LAS bf16x8*)(lds + PG8_SB(b, h) + boff + n * 2048 + k * 1024); } while (0)
; #define PG8_MMA(ai, bj, At, Bt) do { __builtin_amdgcn_s_setprio(1); _Pragma("unroll") for (int m = 0; m < 4; ++m) _Pragma("unroll") for (int n = 0; n < 2; ++n) _Pragma("unroll") for (int k = 0; k < 2; ++k) \
;         acc[ai][bj][m][n] = __builtin_amdgcn_mfma_f32_16x16x32_bf16(Bt[n][k], At[m][k], acc[ai][bj][m][n], 0, 0, 0); __builtin_amdgcn_s_setprio(0); } while (0)
; #define PG8_WAIT_V(n) asm volatile("s_waitcnt vmcnt(" #n ")" ::: "memory")
; #define PG8_WAIT_L(n) asm volatile("s_waitcnt lgkmcnt(" #n ")" ::: "memory")
; #define PG8_BAR __builtin_amdgcn_s_barrier()
; #define PG8_SCHED __builtin_amdgcn_sched_barrier(0)
; template <class EpiT, class Sched>
; __device__ __forceinline__ void gemm_phase(LAS unsigned char* lds, const Gemm g, const Sched& S, const EpiT& E, int wv) {
;     ...
;             PG8_LDB(B0, 0, 0); PG8_LDB(B1, 0, 1); PG8_SCHED; PG8_LDA(At, 0, 0); PG8_STAGE(PG8_SA(1, 1), a1 + hstepA, voffA);
;             PG8_WAIT_V(8); PG8_WAIT_L(0); PG8_BAR; PG8_MMA(0, 0, At, B0); PG8_MMA(0, 1, At, B1); PG8_BAR; PG8_SCHED;
;             PG8_LDA(At, 0, 1); PG8_STAGE(PG8_SB(0, 0), b2, voffB); PG8_STAGE(PG8_SB(0, 1), b2 + hstepB, voffB); PG8_STAGE(PG8_SA(0, 0), a2, voffA);
;             PG8_WAIT_V(8); PG8_WAIT_L(0); PG8_BAR; PG8_MMA(1, 0, At, B0); PG8_MMA(1, 1, At, B1); PG8_BAR; PG8_SCHED;
.LBB0_246:
	s_add_u32 s28, s26, 0xfffc0080
	s_addc_u32 s29, s27, -1
	s_add_i32 s50, 0, 0x10000
	s_cmp_eq_u32 s49, 12
	s_cselect_b32 s31, s19, s29
	s_cselect_b32 s30, s25, s28
	s_cselect_b32 s29, s17, s48
	s_cselect_b32 s28, s46, s47
	s_add_i32 s52, 0, 0x14000
	ds_read_b128 v[128:131], v250
	ds_read_b128 v[132:135], v250 offset:1024
	ds_read_b128 v[146:149], v250 offset:2048
	ds_read_b128 v[150:153], v250 offset:3072
	ds_read_b128 v[154:157], v251
	ds_read_b128 v[158:161], v251 offset:1024
	ds_read_b128 v[166:169], v251 offset:2048
	ds_read_b128 v[170:173], v251 offset:3072
	s_add_i32 m0, s36, 0xc000
	ds_read_b128 v[174:177], v165
	ds_read_b128 v[178:181], v165 offset:1024
	ds_read_b128 v[182:185], v165 offset:2048
	ds_read_b128 v[186:189], v165 offset:3072
	ds_read_b128 v[204:207], v165 offset:4096
	ds_read_b128 v[208:211], v165 offset:5120
	ds_read_b128 v[212:215], v165 offset:6144
	ds_read_b128 v[216:219], v165 offset:7168
	global_load_lds_dwordx4 v142, s[26:27]
	s_add_i32 m0, s36, 0xe000
	s_nop 0
	global_load_lds_dwordx4 v144, s[26:27]
	s_waitcnt vmcnt(8)
	s_waitcnt lgkmcnt(0)
	s_barrier
	s_setprio 1
	v_mfma_f32_16x16x32_bf16 v[124:127], v[128:131], v[174:177], v[124:127]
	v_mfma_f32_16x16x32_bf16 v[120:123], v[146:149], v[174:177], v[120:123]
	v_mfma_f32_16x16x32_bf16 v[116:119], v[128:131], v[182:185], v[116:119]
	v_mfma_f32_16x16x32_bf16 v[112:115], v[146:149], v[182:185], v[112:115]
	v_mfma_f32_16x16x32_bf16 v[108:111], v[128:131], v[204:207], v[108:111]
	v_mfma_f32_16x16x32_bf16 v[104:107], v[146:149], v[204:207], v[104:107]
	v_mfma_f32_16x16x32_bf16 v[100:103], v[128:131], v[212:215], v[100:103]
	v_mfma_f32_16x16x32_bf16 v[96:99], v[146:149], v[212:215], v[96:99]
	v_mfma_f32_16x16x32_bf16 v[124:127], v[132:135], v[178:181], v[124:127]
	v_mfma_f32_16x16x32_bf16 v[120:123], v[150:153], v[178:181], v[120:123]
	v_mfma_f32_16x16x32_bf16 v[116:119], v[132:135], v[186:189], v[116:119]
	v_mfma_f32_16x16x32_bf16 v[112:115], v[150:153], v[186:189], v[112:115]
	v_mfma_f32_16x16x32_bf16 v[108:111], v[132:135], v[208:211], v[108:111]
	v_mfma_f32_16x16x32_bf16 v[104:107], v[150:153], v[208:211], v[104:107]
	v_mfma_f32_16x16x32_bf16 v[100:103], v[132:135], v[216:219], v[100:103]
	v_mfma_f32_16x16x32_bf16 v[96:99], v[150:153], v[216:219], v[96:99]
	v_mfma_f32_16x16x32_bf16 v[64:67], v[154:157], v[174:177], v[64:67]
	v_mfma_f32_16x16x32_bf16 v[56:59], v[166:169], v[174:177], v[56:59]
	v_mfma_f32_16x16x32_bf16 v[52:55], v[154:157], v[182:185], v[52:55]
	v_mfma_f32_16x16x32_bf16 v[48:51], v[166:169], v[182:185], v[48:51]
	v_mfma_f32_16x16x32_bf16 v[44:47], v[154:157], v[204:207], v[44:47]
	v_mfma_f32_16x16x32_bf16 v[40:43], v[166:169], v[204:207], v[40:43]
	v_mfma_f32_16x16x32_bf16 v[36:39], v[154:157], v[212:215], v[36:39]
	v_mfma_f32_16x16x32_bf16 v[32:35], v[166:169], v[212:215], v[32:35]
	v_mfma_f32_16x16x32_bf16 v[64:67], v[158:161], v[178:181], v[64:67]
	v_mfma_f32_16x16x32_bf16 v[56:59], v[170:173], v[178:181], v[56:59]
	v_mfma_f32_16x16x32_bf16 v[52:55], v[158:161], v[186:189], v[52:55]
	v_mfma_f32_16x16x32_bf16 v[48:51], v[170:173], v[186:189], v[48:51]
	v_mfma_f32_16x16x32_bf16 v[44:47], v[158:161], v[208:211], v[44:47]
	v_mfma_f32_16x16x32_bf16 v[40:43], v[170:173], v[208:211], v[40:43]
	v_mfma_f32_16x16x32_bf16 v[36:39], v[158:161], v[216:219], v[36:39]
	v_mfma_f32_16x16x32_bf16 v[32:35], v[170:173], v[216:219], v[32:35]
	s_setprio 0
	s_barrier
	s_add_i32 s50, s50, s35
	s_add_u32 s54, s28, s92
	s_addc_u32 s55, s29, s93
	s_mov_b32 m0, s50
	ds_read_b128 v[174:177], v165 offset:16384
	ds_read_b128 v[178:181], v165 offset:17408
	ds_read_b128 v[182:185], v165 offset:18432
	ds_read_b128 v[186:189], v165 offset:19456
	ds_read_b128 v[204:207], v165 offset:20480
	ds_read_b128 v[208:211], v165 offset:21504
	ds_read_b128 v[212:215], v165 offset:22528
	ds_read_b128 v[216:219], v165 offset:23552
	global_load_lds_dwordx4 v192, s[28:29]
	s_add_i32 m0, s50, 0x2000
	s_add_u32 s50, s28, 0x40000
	s_addc_u32 s51, s29, 0
	s_add_i32 s52, s52, s35
	global_load_lds_dwordx4 v140, s[28:29]
	s_mov_b32 m0, s52
	s_nop 0
	global_load_lds_dwordx4 v192, s[50:51]
	s_add_i32 m0, s52, 0x2000
	s_nop 0
	global_load_lds_dwordx4 v140, s[50:51]
	s_add_u32 s56, s30, s92
	s_addc_u32 s57, s31, s93
	s_mov_b32 m0, s36
	s_nop 0
	global_load_lds_dwordx4 v136, s[30:31]
	s_mov_b32 m0, s37
	s_nop 0
	global_load_lds_dwordx4 v138, s[30:31]
	s_waitcnt vmcnt(8)
	s_waitcnt lgkmcnt(0)
	s_barrier
	s_setprio 1
	v_mfma_f32_16x16x32_bf16 v[92:95], v[128:131], v[174:177], v[92:95]
	v_mfma_f32_16x16x32_bf16 v[88:91], v[146:149], v[174:177], v[88:91]
	v_mfma_f32_16x16x32_bf16 v[84:87], v[128:131], v[182:185], v[84:87]
	v_mfma_f32_16x16x32_bf16 v[80:83], v[146:149], v[182:185], v[80:83]
	v_mfma_f32_16x16x32_bf16 v[76:79], v[128:131], v[204:207], v[76:79]
	v_mfma_f32_16x16x32_bf16 v[72:75], v[146:149], v[204:207], v[72:75]
	v_mfma_f32_16x16x32_bf16 v[68:71], v[128:131], v[212:215], v[68:71]
	v_mfma_f32_16x16x32_bf16 v[60:63], v[146:149], v[212:215], v[60:63]
	v_mfma_f32_16x16x32_bf16 v[92:95], v[132:135], v[178:181], v[92:95]
	v_mfma_f32_16x16x32_bf16 v[88:91], v[150:153], v[178:181], v[88:91]
	v_mfma_f32_16x16x32_bf16 v[84:87], v[132:135], v[186:189], v[84:87]
	v_mfma_f32_16x16x32_bf16 v[80:83], v[150:153], v[186:189], v[80:83]
	v_mfma_f32_16x16x32_bf16 v[76:79], v[132:135], v[208:211], v[76:79]
	v_mfma_f32_16x16x32_bf16 v[72:75], v[150:153], v[208:211], v[72:75]
	v_mfma_f32_16x16x32_bf16 v[68:71], v[132:135], v[216:219], v[68:71]
	v_mfma_f32_16x16x32_bf16 v[60:63], v[150:153], v[216:219], v[60:63]
	v_mfma_f32_16x16x32_bf16 v[28:31], v[154:157], v[174:177], v[28:31]
	v_mfma_f32_16x16x32_bf16 v[24:27], v[166:169], v[174:177], v[24:27]
	v_mfma_f32_16x16x32_bf16 v[20:23], v[154:157], v[182:185], v[20:23]
	v_mfma_f32_16x16x32_bf16 v[16:19], v[166:169], v[182:185], v[16:19]
	v_mfma_f32_16x16x32_bf16 v[12:15], v[154:157], v[204:207], v[12:15]
	v_mfma_f32_16x16x32_bf16 v[8:11], v[166:169], v[204:207], v[8:11]
	v_mfma_f32_16x16x32_bf16 v[4:7], v[154:157], v[212:215], v[4:7]
	v_mfma_f32_16x16x32_bf16 v[0:3], v[166:169], v[212:215], v[0:3]
	v_mfma_f32_16x16x32_bf16 v[28:31], v[158:161], v[178:181], v[28:31]
	v_mfma_f32_16x16x32_bf16 v[24:27], v[170:173], v[178:181], v[24:27]
	v_mfma_f32_16x16x32_bf16 v[20:23], v[158:161], v[186:189], v[20:23]
	v_mfma_f32_16x16x32_bf16 v[16:19], v[170:173], v[186:189], v[16:19]
	v_mfma_f32_16x16x32_bf16 v[12:15], v[158:161], v[208:211], v[12:15]
	v_mfma_f32_16x16x32_bf16 v[8:11], v[170:173], v[208:211], v[8:11]
	v_mfma_f32_16x16x32_bf16 v[4:7], v[158:161], v[216:219], v[4:7]
	v_mfma_f32_16x16x32_bf16 v[0:3], v[170:173], v[216:219], v[0:3]
	s_setprio 0
	s_barrier
; #define PG8_STAGE(bufoff, gbase, voff) do { _Pragma("unroll") for (int _i = 0; _i < 2; ++_i) \
;         __builtin_amdgcn_global_load_lds((const unsigned*)((const char*)(gbase) + (voff)[_i]), (LAS unsigned*)(lds + (bufoff) + ldsw + _i * 8192), 16, 0, 0); } while (0)
; #define PG8_LDA(dst, b, h) do { _Pragma("unroll") for (int m = 0; m < 4; ++m) _Pragma("unroll") for (int k = 0; k < 2; ++k) dst[m][k] = *(const LAS bf16x8*)(lds + PG8_SA(b, h) + aoff + m * 2048 + k * 1024); } while (0)
; #define PG8_LDB(dst, b, h) do { _Pragma("unroll") for (int n = 0; n < 2; ++n) _Pragma("unroll") for (int k = 0; k < 2; ++k) dst[n][k] = *(const LAS bf16x8*)(lds + PG8_SB(b, h) + boff + n * 2048 + k * 1024); } while (0)
; #define PG8_MMA(ai, bj, At, Bt) do { __builtin_amdgcn_s_setprio(1); _Pragma("unroll") for (int m = 0; m < 4; ++m) _Pragma("unroll") for (int n = 0; n < 2; ++n) _Pragma("unroll") for (int k = 0; k < 2; ++k) \
;         acc[ai][bj][m][n] = __builtin_amdgcn_mfma_f32_16x16x32_bf16(Bt[n][k], At[m][k], acc[ai][bj][m][n], 0, 0, 0); __builtin_amdgcn_s_setprio(0); } while (0)
; #define PG8_WAIT_V(n) asm volatile("s_waitcnt vmcnt(" #n ")" ::: "memory")
; #define PG8_WAIT_L(n) asm volatile("s_waitcnt lgkmcnt(" #n ")" ::: "memory")
; #define PG8_BAR __builtin_amdgcn_s_barrier()
; #define PG8_SCHED __builtin_amdgcn_sched_barrier(0)
; template <class EpiT, class Sched>
; __device__ __forceinline__ void gemm_phase(LAS unsigned char* lds, const Gemm g, const Sched& S, const EpiT& E, int wv) {
;     ...
;             PG8_LDB(B0, 1, 0); PG8_LDB(B1, 1, 1); PG8_SCHED; PG8_LDA(At, 1, 0); PG8_STAGE(PG8_SA(0, 1), a2 + hstepA, voffA);
;             PG8_WAIT_V(8); PG8_WAIT_L(0); PG8_BAR; PG8_MMA(0, 0, At, B0); PG8_MMA(0, 1, At, B1); PG8_BAR; PG8_SCHED;
;             PG8_LDA(At, 1, 1); PG8_STAGE(PG8_SB(1, 0), b3, voffB); PG8_STAGE(PG8_SB(1, 1), b3 + hstepB, voffB); PG8_STAGE(PG8_SA(1, 0), a3, voffA);
;             PG8_WAIT_V(8); PG8_WAIT_L(0); PG8_BAR; PG8_MMA(1, 0, At, B0); PG8_MMA(1, 1, At, B1); PG8_BAR; PG8_SCHED;
;         }
;         if (wr == 0) PG8_BAR;
	s_add_i32 s50, 0, 0x18000
	s_add_i32 s51, 0, 0x1c000
	ds_read_b128 v[128:131], v252
	ds_read_b128 v[132:135], v252 offset:1024
	ds_read_b128 v[146:149], v252 offset:2048
	ds_read_b128 v[150:153], v252 offset:3072
	ds_read_b128 v[154:157], v253
	ds_read_b128 v[158:161], v253 offset:1024
	ds_read_b128 v[166:169], v253 offset:2048
	ds_read_b128 v[170:173], v253 offset:3072
	s_add_u32 s30, s30, 0x40000
	s_addc_u32 s31, s31, 0
	s_mov_b32 m0, s38
	ds_read_b128 v[174:177], v165 offset:32768
	ds_read_b128 v[178:181], v165 offset:33792
	ds_read_b128 v[182:185], v165 offset:34816
	ds_read_b128 v[186:189], v165 offset:35840
	ds_read_b128 v[204:207], v165 offset:36864
	ds_read_b128 v[208:211], v165 offset:37888
	ds_read_b128 v[212:215], v165 offset:38912
	ds_read_b128 v[216:219], v165 offset:39936
	global_load_lds_dwordx4 v136, s[30:31]
	s_mov_b32 m0, s39
	s_nop 0
	global_load_lds_dwordx4 v138, s[30:31]
	s_waitcnt vmcnt(8)
	s_waitcnt lgkmcnt(0)
	s_barrier
	s_setprio 1
	v_mfma_f32_16x16x32_bf16 v[124:127], v[128:131], v[174:177], v[124:127]
	v_mfma_f32_16x16x32_bf16 v[120:123], v[146:149], v[174:177], v[120:123]
	v_mfma_f32_16x16x32_bf16 v[116:119], v[128:131], v[182:185], v[116:119]
	v_mfma_f32_16x16x32_bf16 v[112:115], v[146:149], v[182:185], v[112:115]
	v_mfma_f32_16x16x32_bf16 v[108:111], v[128:131], v[204:207], v[108:111]
	v_mfma_f32_16x16x32_bf16 v[104:107], v[146:149], v[204:207], v[104:107]
	v_mfma_f32_16x16x32_bf16 v[100:103], v[128:131], v[212:215], v[100:103]
	v_mfma_f32_16x16x32_bf16 v[96:99], v[146:149], v[212:215], v[96:99]
	v_mfma_f32_16x16x32_bf16 v[124:127], v[132:135], v[178:181], v[124:127]
	v_mfma_f32_16x16x32_bf16 v[120:123], v[150:153], v[178:181], v[120:123]
	v_mfma_f32_16x16x32_bf16 v[116:119], v[132:135], v[186:189], v[116:119]
	v_mfma_f32_16x16x32_bf16 v[112:115], v[150:153], v[186:189], v[112:115]
	v_mfma_f32_16x16x32_bf16 v[108:111], v[132:135], v[208:211], v[108:111]
	v_mfma_f32_16x16x32_bf16 v[104:107], v[150:153], v[208:211], v[104:107]
	v_mfma_f32_16x16x32_bf16 v[100:103], v[132:135], v[216:219], v[100:103]
	v_mfma_f32_16x16x32_bf16 v[96:99], v[150:153], v[216:219], v[96:99]
	v_mfma_f32_16x16x32_bf16 v[64:67], v[154:157], v[174:177], v[64:67]
	v_mfma_f32_16x16x32_bf16 v[56:59], v[166:169], v[174:177], v[56:59]
	v_mfma_f32_16x16x32_bf16 v[52:55], v[154:157], v[182:185], v[52:55]
	v_mfma_f32_16x16x32_bf16 v[48:51], v[166:169], v[182:185], v[48:51]
	v_mfma_f32_16x16x32_bf16 v[44:47], v[154:157], v[204:207], v[44:47]
	v_mfma_f32_16x16x32_bf16 v[40:43], v[166:169], v[204:207], v[40:43]
	v_mfma_f32_16x16x32_bf16 v[36:39], v[154:157], v[212:215], v[36:39]
	v_mfma_f32_16x16x32_bf16 v[32:35], v[166:169], v[212:215], v[32:35]
	v_mfma_f32_16x16x32_bf16 v[64:67], v[158:161], v[178:181], v[64:67]
	v_mfma_f32_16x16x32_bf16 v[56:59], v[170:173], v[178:181], v[56:59]
	v_mfma_f32_16x16x32_bf16 v[52:55], v[158:161], v[186:189], v[52:55]
	v_mfma_f32_16x16x32_bf16 v[48:51], v[170:173], v[186:189], v[48:51]
	v_mfma_f32_16x16x32_bf16 v[44:47], v[158:161], v[208:211], v[44:47]
	v_mfma_f32_16x16x32_bf16 v[40:43], v[170:173], v[208:211], v[40:43]
	v_mfma_f32_16x16x32_bf16 v[36:39], v[158:161], v[216:219], v[36:39]
	v_mfma_f32_16x16x32_bf16 v[32:35], v[170:173], v[216:219], v[32:35]
	s_setprio 0
	s_barrier
	s_add_i32 s30, s50, s35
	s_mov_b32 m0, s30
	ds_read_b128 v[174:177], v165 offset:49152
	ds_read_b128 v[178:181], v165 offset:50176
	ds_read_b128 v[182:185], v165 offset:51200
	ds_read_b128 v[186:189], v165 offset:52224
	ds_read_b128 v[204:207], v165 offset:53248
	ds_read_b128 v[208:211], v165 offset:54272
	ds_read_b128 v[212:215], v165 offset:55296
	ds_read_b128 v[216:219], v165 offset:56320
	global_load_lds_dwordx4 v192, s[54:55]
	s_add_i32 m0, s30, 0x2000
	s_add_u32 s28, s28, 0x40080
	s_addc_u32 s29, s29, 0
	s_add_i32 s30, s51, s35
	global_load_lds_dwordx4 v140, s[54:55]
	s_mov_b32 m0, s30
	s_nop 0
	global_load_lds_dwordx4 v192, s[28:29]
	s_add_i32 m0, s30, 0x2000
	s_nop 0
	global_load_lds_dwordx4 v140, s[28:29]
	s_mov_b32 m0, s40
	s_nop 0
	global_load_lds_dwordx4 v136, s[56:57]
	s_mov_b32 m0, s41
	s_nop 0
	global_load_lds_dwordx4 v138, s[56:57]
	s_waitcnt vmcnt(8)
	s_waitcnt lgkmcnt(0)
	s_barrier
	s_setprio 1
	v_mfma_f32_16x16x32_bf16 v[92:95], v[128:131], v[174:177], v[92:95]
	v_mfma_f32_16x16x32_bf16 v[88:91], v[146:149], v[174:177], v[88:91]
	v_mfma_f32_16x16x32_bf16 v[84:87], v[128:131], v[182:185], v[84:87]
	v_mfma_f32_16x16x32_bf16 v[80:83], v[146:149], v[182:185], v[80:83]
	v_mfma_f32_16x16x32_bf16 v[76:79], v[128:131], v[204:207], v[76:79]
	v_mfma_f32_16x16x32_bf16 v[72:75], v[146:149], v[204:207], v[72:75]
	v_mfma_f32_16x16x32_bf16 v[68:71], v[128:131], v[212:215], v[68:71]
	v_mfma_f32_16x16x32_bf16 v[60:63], v[146:149], v[212:215], v[60:63]
	v_mfma_f32_16x16x32_bf16 v[92:95], v[132:135], v[178:181], v[92:95]
	v_mfma_f32_16x16x32_bf16 v[88:91], v[150:153], v[178:181], v[88:91]
	v_mfma_f32_16x16x32_bf16 v[84:87], v[132:135], v[186:189], v[84:87]
	v_mfma_f32_16x16x32_bf16 v[80:83], v[150:153], v[186:189], v[80:83]
	v_mfma_f32_16x16x32_bf16 v[76:79], v[132:135], v[208:211], v[76:79]
	v_mfma_f32_16x16x32_bf16 v[72:75], v[150:153], v[208:211], v[72:75]
	v_mfma_f32_16x16x32_bf16 v[68:71], v[132:135], v[216:219], v[68:71]
	v_mfma_f32_16x16x32_bf16 v[60:63], v[150:153], v[216:219], v[60:63]
	v_mfma_f32_16x16x32_bf16 v[28:31], v[154:157], v[174:177], v[28:31]
	v_mfma_f32_16x16x32_bf16 v[24:27], v[166:169], v[174:177], v[24:27]
	v_mfma_f32_16x16x32_bf16 v[20:23], v[154:157], v[182:185], v[20:23]
	v_mfma_f32_16x16x32_bf16 v[16:19], v[166:169], v[182:185], v[16:19]
	v_mfma_f32_16x16x32_bf16 v[12:15], v[154:157], v[204:207], v[12:15]
	v_mfma_f32_16x16x32_bf16 v[8:11], v[166:169], v[204:207], v[8:11]
	v_mfma_f32_16x16x32_bf16 v[4:7], v[154:157], v[212:215], v[4:7]
	v_mfma_f32_16x16x32_bf16 v[0:3], v[166:169], v[212:215], v[0:3]
	v_mfma_f32_16x16x32_bf16 v[28:31], v[158:161], v[178:181], v[28:31]
	v_mfma_f32_16x16x32_bf16 v[24:27], v[170:173], v[178:181], v[24:27]
	v_mfma_f32_16x16x32_bf16 v[20:23], v[158:161], v[186:189], v[20:23]
	v_mfma_f32_16x16x32_bf16 v[16:19], v[170:173], v[186:189], v[16:19]
	v_mfma_f32_16x16x32_bf16 v[12:15], v[158:161], v[208:211], v[12:15]
	v_mfma_f32_16x16x32_bf16 v[8:11], v[170:173], v[208:211], v[8:11]
	v_mfma_f32_16x16x32_bf16 v[4:7], v[158:161], v[216:219], v[4:7]
	v_mfma_f32_16x16x32_bf16 v[0:3], v[170:173], v[216:219], v[0:3]
	s_setprio 0
	s_barrier
	s_add_i32 s49, s49, 2
	s_add_u32 s26, s26, 0x100
	s_addc_u32 s27, s27, 0
	s_add_u32 s47, s47, 0x100
	s_addc_u32 s48, s48, 0
	s_cmp_gt_u32 s49, 13
	s_cbranch_scc0 .LBB0_246
	s_and_b64 vcc, exec, s[12:13]
	s_cbranch_vccz .LBB0_249
	s_barrier

; #define PG8_STAGE(bufoff, gbase, voff) do { _Pragma("unroll") for (int _i = 0; _i < 2; ++_i) \
;         __builtin_amdgcn_global_load_lds((const unsigned*)((const char*)(gbase) + (voff)[_i]), (LAS unsigned*)(lds + (bufoff) + ldsw + _i * 8192), 16, 0, 0); } while (0)
; #define PG8_LDA(dst, b, h) do { _Pragma("unroll") for (int m = 0; m < 4; ++m) _Pragma("unroll") for (int k = 0; k < 2; ++k) dst[m][k] = *(const LAS bf16x8*)(lds + PG8_SA(b, h) + aoff + m * 2048 + k * 1024); } while (0)
; #define PG8_LDB(dst, b, h) do { _Pragma("unroll") for (int n = 0; n < 2; ++n) _Pragma("unroll") for (int k = 0; k < 2; ++k) dst[n][k] = *(const LAS bf16x8*)(lds + PG8_SB(b, h) + boff + n * 2048 + k * 1024); } while (0)
; #define PG8_MMA(ai, bj, At, Bt) do { __builtin_amdgcn_s_setprio(1); _Pragma("unroll") for (int m = 0; m < 4; ++m) _Pragma("unroll") for (int n = 0; n < 2; ++n) _Pragma("unroll") for (int k = 0; k < 2; ++k) \
;         acc[ai][bj][m][n] = __builtin_amdgcn_mfma_f32_16x16x32_bf16(Bt[n][k], At[m][k], acc[ai][bj][m][n], 0, 0, 0); __builtin_amdgcn_s_setprio(0); } while (0)
; #define PG8_WAIT_V(n) asm volatile("s_waitcnt vmcnt(" #n ")" ::: "memory")
; #define PG8_WAIT_L(n) asm volatile("s_waitcnt lgkmcnt(" #n ")" ::: "memory")
; #define PG8_BAR __builtin_amdgcn_s_barrier()
; #define PG8_SCHED __builtin_amdgcn_sched_barrier(0)
; template <class EpiT, class Sched>
; __device__ __forceinline__ void gemm_phase(LAS unsigned char* lds, const Gemm g, const Sched& S, const EpiT& E, int wv) {
;     ...
;             const bool last = (t == nt - 2);
;             const char* a1 = cA + (size_t)(t + 1) * kstep;
;             const char* a2 = last ? nA : cA + (size_t)(t + 2) * kstep; const char* b2 = last ? nB : cB + (size_t)(t + 2) * kstep;
;             const char* a3 = a2 + kstep; const char* b3 = b2 + kstep;
;             PG8_LDB(B0, 0, 0); PG8_LDB(B1, 0, 1); PG8_SCHED; PG8_LDA(At, 0, 0); PG8_STAGE(PG8_SA(1, 1), a1 + hstepA, voffA);
;             PG8_WAIT_V(8); PG8_WAIT_L(0); PG8_BAR; PG8_MMA(0, 0, At, B0); PG8_MMA(0, 1, At, B1); PG8_BAR; PG8_SCHED;
;             PG8_LDA(At, 0, 1); PG8_STAGE(PG8_SB(0, 0), b2, voffB); PG8_STAGE(PG8_SB(0, 1), b2 + hstepB, voffB); PG8_STAGE(PG8_SA(0, 0), a2, voffA);
;             PG8_WAIT_V(8); PG8_WAIT_L(0); PG8_BAR; PG8_MMA(1, 0, At, B0); PG8_MMA(1, 1, At, B1); PG8_BAR; PG8_SCHED;
.LBB0_472:
	s_add_i32 s9, s4, 2
	s_add_u32 s11, s0, 0x80
	s_addc_u32 s5, s1, 0
	s_add_i32 s33, 0, 0x10000
	s_cmp_eq_u32 s58, s4
	s_cselect_b32 s5, s35, s5
	s_cselect_b32 s4, s34, s11
	s_cselect_b32 s39, s37, s7
	s_cselect_b32 s38, s36, s6
	s_add_i32 s11, 0, 0x14000
	ds_read_b128 v[128:131], v250
	ds_read_b128 v[142:145], v250 offset:1024
	ds_read_b128 v[146:149], v250 offset:2048
	ds_read_b128 v[150:153], v250 offset:3072
	ds_read_b128 v[154:157], v251
	ds_read_b128 v[160:163], v251 offset:1024
	ds_read_b128 v[164:167], v251 offset:2048
	ds_read_b128 v[168:171], v251 offset:3072
	v_lshl_add_u64 v[216:217], s[0:1], 0, v[138:139]
	s_add_i32 m0, s50, 0xc000
	ds_read_b128 v[172:175], v159
	ds_read_b128 v[176:179], v159 offset:1024
	ds_read_b128 v[180:183], v159 offset:2048
	ds_read_b128 v[184:187], v159 offset:3072
	ds_read_b128 v[188:191], v159 offset:4096
	ds_read_b128 v[204:207], v159 offset:5120
	ds_read_b128 v[208:211], v159 offset:6144
	ds_read_b128 v[212:215], v159 offset:7168
	global_load_lds_dwordx4 v[216:217], off
	v_lshl_add_u64 v[216:217], s[0:1], 0, v[140:141]
	s_add_i32 m0, s50, 0xe000
	s_nop 0
	global_load_lds_dwordx4 v[216:217], off
	s_waitcnt vmcnt(8)
	s_waitcnt lgkmcnt(0)
	s_barrier
	s_setprio 1
	v_mfma_f32_16x16x32_bf16 v[120:123], v[128:131], v[172:175], v[120:123]
	v_mfma_f32_16x16x32_bf16 v[124:127], v[146:149], v[172:175], v[124:127]
	v_mfma_f32_16x16x32_bf16 v[116:119], v[128:131], v[180:183], v[116:119]
	v_mfma_f32_16x16x32_bf16 v[112:115], v[146:149], v[180:183], v[112:115]
	v_mfma_f32_16x16x32_bf16 v[108:111], v[128:131], v[188:191], v[108:111]
	v_mfma_f32_16x16x32_bf16 v[104:107], v[146:149], v[188:191], v[104:107]
	v_mfma_f32_16x16x32_bf16 v[100:103], v[128:131], v[208:211], v[100:103]
	v_mfma_f32_16x16x32_bf16 v[96:99], v[146:149], v[208:211], v[96:99]
	v_mfma_f32_16x16x32_bf16 v[120:123], v[142:145], v[176:179], v[120:123]
	v_mfma_f32_16x16x32_bf16 v[124:127], v[150:153], v[176:179], v[124:127]
	v_mfma_f32_16x16x32_bf16 v[116:119], v[142:145], v[184:187], v[116:119]
	v_mfma_f32_16x16x32_bf16 v[112:115], v[150:153], v[184:187], v[112:115]
	v_mfma_f32_16x16x32_bf16 v[108:111], v[142:145], v[204:207], v[108:111]
	v_mfma_f32_16x16x32_bf16 v[104:107], v[150:153], v[204:207], v[104:107]
	v_mfma_f32_16x16x32_bf16 v[100:103], v[142:145], v[212:215], v[100:103]
	v_mfma_f32_16x16x32_bf16 v[96:99], v[150:153], v[212:215], v[96:99]
	v_mfma_f32_16x16x32_bf16 v[60:63], v[154:157], v[172:175], v[60:63]
	v_mfma_f32_16x16x32_bf16 v[56:59], v[164:167], v[172:175], v[56:59]
	v_mfma_f32_16x16x32_bf16 v[52:55], v[154:157], v[180:183], v[52:55]
	v_mfma_f32_16x16x32_bf16 v[48:51], v[164:167], v[180:183], v[48:51]
	v_mfma_f32_16x16x32_bf16 v[44:47], v[154:157], v[188:191], v[44:47]
	v_mfma_f32_16x16x32_bf16 v[40:43], v[164:167], v[188:191], v[40:43]
	v_mfma_f32_16x16x32_bf16 v[36:39], v[154:157], v[208:211], v[36:39]
	v_mfma_f32_16x16x32_bf16 v[32:35], v[164:167], v[208:211], v[32:35]
	v_mfma_f32_16x16x32_bf16 v[60:63], v[160:163], v[176:179], v[60:63]
	v_mfma_f32_16x16x32_bf16 v[56:59], v[168:171], v[176:179], v[56:59]
	v_mfma_f32_16x16x32_bf16 v[52:55], v[160:163], v[184:187], v[52:55]
	v_mfma_f32_16x16x32_bf16 v[48:51], v[168:171], v[184:187], v[48:51]
	v_mfma_f32_16x16x32_bf16 v[44:47], v[160:163], v[204:207], v[44:47]
	v_mfma_f32_16x16x32_bf16 v[40:43], v[168:171], v[204:207], v[40:43]
	v_mfma_f32_16x16x32_bf16 v[36:39], v[160:163], v[212:215], v[36:39]
	v_mfma_f32_16x16x32_bf16 v[32:35], v[168:171], v[212:215], v[32:35]
	s_setprio 0
	s_barrier
	s_add_i32 s33, s33, s49
	v_lshl_add_u64 v[216:217], s[38:39], 0, v[192:193]
	s_mov_b32 m0, s33
	ds_read_b128 v[172:175], v159 offset:16384
	ds_read_b128 v[176:179], v159 offset:17408
	ds_read_b128 v[180:183], v159 offset:18432
	ds_read_b128 v[184:187], v159 offset:19456
	ds_read_b128 v[188:191], v159 offset:20480
	ds_read_b128 v[204:207], v159 offset:21504
	ds_read_b128 v[208:211], v159 offset:22528
	ds_read_b128 v[212:215], v159 offset:23552
	global_load_lds_dwordx4 v[216:217], off
	s_add_i32 m0, s33, 0x2000
	v_lshl_add_u64 v[218:219], s[38:39], 0, v[136:137]
	s_add_u32 s38, s38, s16
	s_addc_u32 s39, s39, s17
	s_add_i32 s11, s11, s49
	global_load_lds_dwordx4 v[218:219], off
	v_lshl_add_u64 v[220:221], s[38:39], 0, v[192:193]
	s_mov_b32 m0, s11
	v_lshl_add_u64 v[222:223], s[38:39], 0, v[136:137]
	global_load_lds_dwordx4 v[220:221], off
	s_add_i32 m0, s11, 0x2000
	v_lshl_add_u64 v[232:233], s[4:5], 0, v[132:133]
	global_load_lds_dwordx4 v[222:223], off
	s_mov_b32 m0, s50
	v_lshl_add_u64 v[234:235], s[4:5], 0, v[134:135]
	global_load_lds_dwordx4 v[232:233], off
	s_mov_b32 m0, s51
	s_nop 0
	global_load_lds_dwordx4 v[234:235], off
	s_waitcnt vmcnt(8)
	s_waitcnt lgkmcnt(0)
	s_barrier
; #define PG8_STAGE(bufoff, gbase, voff) do { _Pragma("unroll") for (int _i = 0; _i < 2; ++_i) \
;         __builtin_amdgcn_global_load_lds((const unsigned*)((const char*)(gbase) + (voff)[_i]), (LAS unsigned*)(lds + (bufoff) + ldsw + _i * 8192), 16, 0, 0); } while (0)
; #define PG8_LDA(dst, b, h) do { _Pragma("unroll") for (int m = 0; m < 4; ++m) _Pragma("unroll") for (int k = 0; k < 2; ++k) dst[m][k] = *(const LAS bf16x8*)(lds + PG8_SA(b, h) + aoff + m * 2048 + k * 1024); } while (0)
; #define PG8_LDB(dst, b, h) do { _Pragma("unroll") for (int n = 0; n < 2; ++n) _Pragma("unroll") for (int k = 0; k < 2; ++k) dst[n][k] = *(const LAS bf16x8*)(lds + PG8_SB(b, h) + boff + n * 2048 + k * 1024); } while (0)
; #define PG8_MMA(ai, bj, At, Bt) do { __builtin_amdgcn_s_setprio(1); _Pragma("unroll") for (int m = 0; m < 4; ++m) _Pragma("unroll") for (int n = 0; n < 2; ++n) _Pragma("unroll") for (int k = 0; k < 2; ++k) \
;         acc[ai][bj][m][n] = __builtin_amdgcn_mfma_f32_16x16x32_bf16(Bt[n][k], At[m][k], acc[ai][bj][m][n], 0, 0, 0); __builtin_amdgcn_s_setprio(0); } while (0)
; #define PG8_WAIT_V(n) asm volatile("s_waitcnt vmcnt(" #n ")" ::: "memory")
; #define PG8_WAIT_L(n) asm volatile("s_waitcnt lgkmcnt(" #n ")" ::: "memory")
; #define PG8_BAR __builtin_amdgcn_s_barrier()
; #define PG8_SCHED __builtin_amdgcn_sched_barrier(0)
; template <class EpiT, class Sched>
; __device__ __forceinline__ void gemm_phase(LAS unsigned char* lds, const Gemm g, const Sched& S, const EpiT& E, int wv) {
;     ...
;             PG8_WAIT_V(8); PG8_WAIT_L(0); PG8_BAR; PG8_MMA(1, 0, At, B0); PG8_MMA(1, 1, At, B1); PG8_BAR; PG8_SCHED;
;             PG8_LDB(B0, 1, 0); PG8_LDB(B1, 1, 1); PG8_SCHED; PG8_LDA(At, 1, 0); PG8_STAGE(PG8_SA(0, 1), a2 + hstepA, voffA);
;             PG8_WAIT_V(8); PG8_WAIT_L(0); PG8_BAR; PG8_MMA(0, 0, At, B0); PG8_MMA(0, 1, At, B1); PG8_BAR; PG8_SCHED;
	s_setprio 1
	v_mfma_f32_16x16x32_bf16 v[92:95], v[128:131], v[172:175], v[92:95]
	v_mfma_f32_16x16x32_bf16 v[88:91], v[146:149], v[172:175], v[88:91]
	v_mfma_f32_16x16x32_bf16 v[84:87], v[128:131], v[180:183], v[84:87]
	v_mfma_f32_16x16x32_bf16 v[80:83], v[146:149], v[180:183], v[80:83]
	v_mfma_f32_16x16x32_bf16 v[76:79], v[128:131], v[188:191], v[76:79]
	v_mfma_f32_16x16x32_bf16 v[72:75], v[146:149], v[188:191], v[72:75]
	v_mfma_f32_16x16x32_bf16 v[68:71], v[128:131], v[208:211], v[68:71]
	v_mfma_f32_16x16x32_bf16 v[64:67], v[146:149], v[208:211], v[64:67]
	v_mfma_f32_16x16x32_bf16 v[92:95], v[142:145], v[176:179], v[92:95]
	v_mfma_f32_16x16x32_bf16 v[88:91], v[150:153], v[176:179], v[88:91]
	v_mfma_f32_16x16x32_bf16 v[84:87], v[142:145], v[184:187], v[84:87]
	v_mfma_f32_16x16x32_bf16 v[80:83], v[150:153], v[184:187], v[80:83]
	v_mfma_f32_16x16x32_bf16 v[76:79], v[142:145], v[204:207], v[76:79]
	v_mfma_f32_16x16x32_bf16 v[72:75], v[150:153], v[204:207], v[72:75]
	v_mfma_f32_16x16x32_bf16 v[68:71], v[142:145], v[212:215], v[68:71]
	v_mfma_f32_16x16x32_bf16 v[64:67], v[150:153], v[212:215], v[64:67]
	v_mfma_f32_16x16x32_bf16 v[28:31], v[154:157], v[172:175], v[28:31]
	v_mfma_f32_16x16x32_bf16 v[24:27], v[164:167], v[172:175], v[24:27]
	v_mfma_f32_16x16x32_bf16 v[20:23], v[154:157], v[180:183], v[20:23]
	v_mfma_f32_16x16x32_bf16 v[16:19], v[164:167], v[180:183], v[16:19]
	v_mfma_f32_16x16x32_bf16 v[12:15], v[154:157], v[188:191], v[12:15]
	v_mfma_f32_16x16x32_bf16 v[8:11], v[164:167], v[188:191], v[8:11]
	v_mfma_f32_16x16x32_bf16 v[4:7], v[154:157], v[208:211], v[4:7]
	v_mfma_f32_16x16x32_bf16 v[0:3], v[164:167], v[208:211], v[0:3]
	v_mfma_f32_16x16x32_bf16 v[28:31], v[160:163], v[176:179], v[28:31]
	v_mfma_f32_16x16x32_bf16 v[24:27], v[168:171], v[176:179], v[24:27]
	v_mfma_f32_16x16x32_bf16 v[20:23], v[160:163], v[184:187], v[20:23]
	v_mfma_f32_16x16x32_bf16 v[16:19], v[168:171], v[184:187], v[16:19]
	v_mfma_f32_16x16x32_bf16 v[12:15], v[160:163], v[204:207], v[12:15]
	v_mfma_f32_16x16x32_bf16 v[8:11], v[168:171], v[204:207], v[8:11]
	v_mfma_f32_16x16x32_bf16 v[4:7], v[160:163], v[212:215], v[4:7]
	v_mfma_f32_16x16x32_bf16 v[0:3], v[168:171], v[212:215], v[0:3]
	s_setprio 0
	s_barrier
	s_add_i32 s11, 0, 0x18000
	s_add_i32 s33, 0, 0x1c000
	ds_read_b128 v[128:131], v252
	ds_read_b128 v[142:145], v252 offset:1024
	ds_read_b128 v[146:149], v252 offset:2048
	ds_read_b128 v[150:153], v252 offset:3072
	ds_read_b128 v[154:157], v253
	ds_read_b128 v[160:163], v253 offset:1024
	ds_read_b128 v[164:167], v253 offset:2048
	ds_read_b128 v[168:171], v253 offset:3072
	s_add_u32 s4, s4, s16
	s_addc_u32 s5, s5, s17
	s_mov_b32 m0, s52
	v_lshl_add_u64 v[240:241], s[4:5], 0, v[132:133]
	ds_read_b128 v[172:175], v159 offset:32768
	ds_read_b128 v[176:179], v159 offset:33792
	ds_read_b128 v[180:183], v159 offset:34816
	ds_read_b128 v[184:187], v159 offset:35840
	ds_read_b128 v[188:191], v159 offset:36864
	ds_read_b128 v[204:207], v159 offset:37888
	ds_read_b128 v[208:211], v159 offset:38912
	ds_read_b128 v[212:215], v159 offset:39936
	global_load_lds_dwordx4 v[240:241], off
	v_lshl_add_u64 v[240:241], s[4:5], 0, v[134:135]
	s_mov_b32 m0, s53
	s_nop 0
	global_load_lds_dwordx4 v[240:241], off
	s_waitcnt vmcnt(8)
	s_waitcnt lgkmcnt(0)
	s_barrier
	s_setprio 1
	v_mfma_f32_16x16x32_bf16 v[120:123], v[128:131], v[172:175], v[120:123]
	v_mfma_f32_16x16x32_bf16 v[124:127], v[146:149], v[172:175], v[124:127]
	v_mfma_f32_16x16x32_bf16 v[116:119], v[128:131], v[180:183], v[116:119]
	v_mfma_f32_16x16x32_bf16 v[112:115], v[146:149], v[180:183], v[112:115]
	v_mfma_f32_16x16x32_bf16 v[108:111], v[128:131], v[188:191], v[108:111]
	v_mfma_f32_16x16x32_bf16 v[104:107], v[146:149], v[188:191], v[104:107]
	v_mfma_f32_16x16x32_bf16 v[100:103], v[128:131], v[208:211], v[100:103]
	v_mfma_f32_16x16x32_bf16 v[96:99], v[146:149], v[208:211], v[96:99]
	v_mfma_f32_16x16x32_bf16 v[120:123], v[142:145], v[176:179], v[120:123]
	v_mfma_f32_16x16x32_bf16 v[124:127], v[150:153], v[176:179], v[124:127]
	v_mfma_f32_16x16x32_bf16 v[116:119], v[142:145], v[184:187], v[116:119]
	v_mfma_f32_16x16x32_bf16 v[112:115], v[150:153], v[184:187], v[112:115]
	v_mfma_f32_16x16x32_bf16 v[108:111], v[142:145], v[204:207], v[108:111]
	v_mfma_f32_16x16x32_bf16 v[104:107], v[150:153], v[204:207], v[104:107]
	v_mfma_f32_16x16x32_bf16 v[100:103], v[142:145], v[212:215], v[100:103]
	v_mfma_f32_16x16x32_bf16 v[96:99], v[150:153], v[212:215], v[96:99]
	v_mfma_f32_16x16x32_bf16 v[60:63], v[154:157], v[172:175], v[60:63]
	v_mfma_f32_16x16x32_bf16 v[56:59], v[164:167], v[172:175], v[56:59]
	v_mfma_f32_16x16x32_bf16 v[52:55], v[154:157], v[180:183], v[52:55]
	v_mfma_f32_16x16x32_bf16 v[48:51], v[164:167], v[180:183], v[48:51]
	v_mfma_f32_16x16x32_bf16 v[44:47], v[154:157], v[188:191], v[44:47]
	v_mfma_f32_16x16x32_bf16 v[40:43], v[164:167], v[188:191], v[40:43]
	v_mfma_f32_16x16x32_bf16 v[36:39], v[154:157], v[208:211], v[36:39]
	v_mfma_f32_16x16x32_bf16 v[32:35], v[164:167], v[208:211], v[32:35]
	v_mfma_f32_16x16x32_bf16 v[60:63], v[160:163], v[176:179], v[60:63]
	v_mfma_f32_16x16x32_bf16 v[56:59], v[168:171], v[176:179], v[56:59]
	v_mfma_f32_16x16x32_bf16 v[52:55], v[160:163], v[184:187], v[52:55]
	v_mfma_f32_16x16x32_bf16 v[48:51], v[168:171], v[184:187], v[48:51]
	v_mfma_f32_16x16x32_bf16 v[44:47], v[160:163], v[204:207], v[44:47]
	v_mfma_f32_16x16x32_bf16 v[40:43], v[168:171], v[204:207], v[40:43]
	v_mfma_f32_16x16x32_bf16 v[36:39], v[160:163], v[212:215], v[36:39]
	v_mfma_f32_16x16x32_bf16 v[32:35], v[168:171], v[212:215], v[32:35]
	s_setprio 0
	s_barrier
; #define PG8_STAGE(bufoff, gbase, voff) do { _Pragma("unroll") for (int _i = 0; _i < 2; ++_i) \
;         __builtin_amdgcn_global_load_lds((const unsigned*)((const char*)(gbase) + (voff)[_i]), (LAS unsigned*)(lds + (bufoff) + ldsw + _i * 8192), 16, 0, 0); } while (0)
; #define PG8_LDA(dst, b, h) do { _Pragma("unroll") for (int m = 0; m < 4; ++m) _Pragma("unroll") for (int k = 0; k < 2; ++k) dst[m][k] = *(const LAS bf16x8*)(lds + PG8_SA(b, h) + aoff + m * 2048 + k * 1024); } while (0)
; #define PG8_MMA(ai, bj, At, Bt) do { __builtin_amdgcn_s_setprio(1); _Pragma("unroll") for (int m = 0; m < 4; ++m) _Pragma("unroll") for (int n = 0; n < 2; ++n) _Pragma("unroll") for (int k = 0; k < 2; ++k) \
;         acc[ai][bj][m][n] = __builtin_amdgcn_mfma_f32_16x16x32_bf16(Bt[n][k], At[m][k], acc[ai][bj][m][n], 0, 0, 0); __builtin_amdgcn_s_setprio(0); } while (0)
; #define PG8_WAIT_V(n) asm volatile("s_waitcnt vmcnt(" #n ")" ::: "memory")
; #define PG8_WAIT_L(n) asm volatile("s_waitcnt lgkmcnt(" #n ")" ::: "memory")
; #define PG8_BAR __builtin_amdgcn_s_barrier()
; #define PG8_SCHED __builtin_amdgcn_sched_barrier(0)
; template <class EpiT, class Sched>
; __device__ __forceinline__ void gemm_phase(LAS unsigned char* lds, const Gemm g, const Sched& S, const EpiT& E, int wv) {
;     ...
;             PG8_LDA(At, 1, 1); PG8_STAGE(PG8_SB(1, 0), b3, voffB); PG8_STAGE(PG8_SB(1, 1), b3 + hstepB, voffB); PG8_STAGE(PG8_SA(1, 0), a3, voffA);
;             PG8_WAIT_V(8); PG8_WAIT_L(0); PG8_BAR; PG8_MMA(1, 0, At, B0); PG8_MMA(1, 1, At, B1); PG8_BAR; PG8_SCHED;
;         }
	s_add_i32 s4, s11, s49
	v_lshl_add_u64 v[216:217], v[216:217], 0, s[92:93]
	s_mov_b32 m0, s4
	ds_read_b128 v[172:175], v159 offset:49152
	ds_read_b128 v[176:179], v159 offset:50176
	ds_read_b128 v[180:183], v159 offset:51200
	ds_read_b128 v[184:187], v159 offset:52224
	ds_read_b128 v[188:191], v159 offset:53248
	ds_read_b128 v[204:207], v159 offset:54272
	ds_read_b128 v[208:211], v159 offset:55296
	ds_read_b128 v[212:215], v159 offset:56320
	global_load_lds_dwordx4 v[216:217], off
	v_lshl_add_u64 v[216:217], v[218:219], 0, s[92:93]
	s_add_i32 m0, s4, 0x2000
	s_add_i32 s4, s33, s49
	global_load_lds_dwordx4 v[216:217], off
	v_lshl_add_u64 v[216:217], v[220:221], 0, s[92:93]
	s_mov_b32 m0, s4
	s_nop 0
	global_load_lds_dwordx4 v[216:217], off
	v_lshl_add_u64 v[216:217], v[222:223], 0, s[92:93]
	s_add_i32 m0, s4, 0x2000
	s_nop 0
	global_load_lds_dwordx4 v[216:217], off
	v_lshl_add_u64 v[216:217], v[232:233], 0, s[92:93]
	s_mov_b32 m0, s54
	s_nop 0
	global_load_lds_dwordx4 v[216:217], off
	v_lshl_add_u64 v[216:217], v[234:235], 0, s[92:93]
	s_mov_b32 m0, s55
	s_nop 0
	global_load_lds_dwordx4 v[216:217], off
	s_waitcnt vmcnt(8)
	s_waitcnt lgkmcnt(0)
	s_barrier
	s_setprio 1
	v_mfma_f32_16x16x32_bf16 v[92:95], v[128:131], v[172:175], v[92:95]
	v_mfma_f32_16x16x32_bf16 v[88:91], v[146:149], v[172:175], v[88:91]
	v_mfma_f32_16x16x32_bf16 v[84:87], v[128:131], v[180:183], v[84:87]
	v_mfma_f32_16x16x32_bf16 v[80:83], v[146:149], v[180:183], v[80:83]
	v_mfma_f32_16x16x32_bf16 v[76:79], v[128:131], v[188:191], v[76:79]
	v_mfma_f32_16x16x32_bf16 v[72:75], v[146:149], v[188:191], v[72:75]
	v_mfma_f32_16x16x32_bf16 v[68:71], v[128:131], v[208:211], v[68:71]
	v_mfma_f32_16x16x32_bf16 v[64:67], v[146:149], v[208:211], v[64:67]
	v_mfma_f32_16x16x32_bf16 v[92:95], v[142:145], v[176:179], v[92:95]
	v_mfma_f32_16x16x32_bf16 v[88:91], v[150:153], v[176:179], v[88:91]
	v_mfma_f32_16x16x32_bf16 v[84:87], v[142:145], v[184:187], v[84:87]
	v_mfma_f32_16x16x32_bf16 v[80:83], v[150:153], v[184:187], v[80:83]
	v_mfma_f32_16x16x32_bf16 v[76:79], v[142:145], v[204:207], v[76:79]
	v_mfma_f32_16x16x32_bf16 v[72:75], v[150:153], v[204:207], v[72:75]
	v_mfma_f32_16x16x32_bf16 v[68:71], v[142:145], v[212:215], v[68:71]
	v_mfma_f32_16x16x32_bf16 v[64:67], v[150:153], v[212:215], v[64:67]
	v_mfma_f32_16x16x32_bf16 v[28:31], v[154:157], v[172:175], v[28:31]
	v_mfma_f32_16x16x32_bf16 v[24:27], v[164:167], v[172:175], v[24:27]
	v_mfma_f32_16x16x32_bf16 v[20:23], v[154:157], v[180:183], v[20:23]
	v_mfma_f32_16x16x32_bf16 v[16:19], v[164:167], v[180:183], v[16:19]
	v_mfma_f32_16x16x32_bf16 v[12:15], v[154:157], v[188:191], v[12:15]
	v_mfma_f32_16x16x32_bf16 v[8:11], v[164:167], v[188:191], v[8:11]
	v_mfma_f32_16x16x32_bf16 v[4:7], v[154:157], v[208:211], v[4:7]
	v_mfma_f32_16x16x32_bf16 v[0:3], v[164:167], v[208:211], v[0:3]
	v_mfma_f32_16x16x32_bf16 v[28:31], v[160:163], v[176:179], v[28:31]
	v_mfma_f32_16x16x32_bf16 v[24:27], v[168:171], v[176:179], v[24:27]
	v_mfma_f32_16x16x32_bf16 v[20:23], v[160:163], v[184:187], v[20:23]
	v_mfma_f32_16x16x32_bf16 v[16:19], v[168:171], v[184:187], v[16:19]
	v_mfma_f32_16x16x32_bf16 v[12:15], v[160:163], v[204:207], v[12:15]
	v_mfma_f32_16x16x32_bf16 v[8:11], v[168:171], v[204:207], v[8:11]
	v_mfma_f32_16x16x32_bf16 v[4:7], v[160:163], v[212:215], v[4:7]
	v_mfma_f32_16x16x32_bf16 v[0:3], v[168:171], v[212:215], v[0:3]
	s_setprio 0
	s_barrier
	s_add_u32 s0, s0, 0x100
	s_addc_u32 s1, s1, 0
	s_add_u32 s6, s6, 0x100
	s_addc_u32 s7, s7, 0
	s_cmp_ge_i32 s9, s57
	s_mov_b32 s4, s9
	s_cbranch_scc0 .LBB0_472

; #define PG8_STAGE(bufoff, gbase, voff) do { _Pragma("unroll") for (int _i = 0; _i < 2; ++_i) \
;         __builtin_amdgcn_global_load_lds((const unsigned*)((const char*)(gbase) + (voff)[_i]), (LAS unsigned*)(lds + (bufoff) + ldsw + _i * 8192), 16, 0, 0); } while (0)
; #define PG8_LDA(dst, b, h) do { _Pragma("unroll") for (int m = 0; m < 4; ++m) _Pragma("unroll") for (int k = 0; k < 2; ++k) dst[m][k] = *(const LAS bf16x8*)(lds + PG8_SA(b, h) + aoff + m * 2048 + k * 1024); } while (0)
; #define PG8_LDB(dst, b, h) do { _Pragma("unroll") for (int n = 0; n < 2; ++n) _Pragma("unroll") for (int k = 0; k < 2; ++k) dst[n][k] = *(const LAS bf16x8*)(lds + PG8_SB(b, h) + boff + n * 2048 + k * 1024); } while (0)
; #define PG8_MMA(ai, bj, At, Bt) do { __builtin_amdgcn_s_setprio(1); _Pragma("unroll") for (int m = 0; m < 4; ++m) _Pragma("unroll") for (int n = 0; n < 2; ++n) _Pragma("unroll") for (int k = 0; k < 2; ++k) \
;         acc[ai][bj][m][n] = __builtin_amdgcn_mfma_f32_16x16x32_bf16(Bt[n][k], At[m][k], acc[ai][bj][m][n], 0, 0, 0); __builtin_amdgcn_s_setprio(0); } while (0)
; #define PG8_WAIT_V(n) asm volatile("s_waitcnt vmcnt(" #n ")" ::: "memory")
; #define PG8_WAIT_L(n) asm volatile("s_waitcnt lgkmcnt(" #n ")" ::: "memory")
; #define PG8_BAR __builtin_amdgcn_s_barrier()
; #define PG8_SCHED __builtin_amdgcn_sched_barrier(0)
; template <class EpiT, class Sched>
; __device__ __forceinline__ void gemm_phase(LAS unsigned char* lds, const Gemm g, const Sched& S, const EpiT& E, int wv) {
;     ...
;             const bool last = (t == nt - 2);
;             const char* a1 = cA + (size_t)(t + 1) * kstep;
;             const char* a2 = last ? nA : cA + (size_t)(t + 2) * kstep; const char* b2 = last ? nB : cB + (size_t)(t + 2) * kstep;
;             const char* a3 = a2 + kstep; const char* b3 = b2 + kstep;
;             PG8_LDB(B0, 0, 0); PG8_LDB(B1, 0, 1); PG8_SCHED; PG8_LDA(At, 0, 0); PG8_STAGE(PG8_SA(1, 1), a1 + hstepA, voffA);
;             PG8_WAIT_V(8); PG8_WAIT_L(0); PG8_BAR; PG8_MMA(0, 0, At, B0); PG8_MMA(0, 1, At, B1); PG8_BAR; PG8_SCHED;
;             PG8_LDA(At, 0, 1); PG8_STAGE(PG8_SB(0, 0), b2, voffB); PG8_STAGE(PG8_SB(0, 1), b2 + hstepB, voffB); PG8_STAGE(PG8_SA(0, 0), a2, voffA);
;             PG8_WAIT_V(8); PG8_WAIT_L(0); PG8_BAR; PG8_MMA(1, 0, At, B0); PG8_MMA(1, 1, At, B1); PG8_BAR; PG8_SCHED;
.LBB0_623:
	s_add_i32 s39, s4, 2
	s_add_u32 s63, s0, 0x80
	s_addc_u32 s5, s1, 0
	s_add_i32 s67, 0, 0x10000
	s_cmp_eq_u32 s53, s4
	s_cselect_b32 s5, s31, s5
	s_cselect_b32 s4, s30, s63
	s_cselect_b32 s65, s35, s37
	s_cselect_b32 s64, s34, s36
	s_add_i32 s63, 0, 0x14000
	ds_read_b128 v[128:131], v250
	ds_read_b128 v[132:135], v250 offset:1024
	ds_read_b128 v[136:139], v250 offset:2048
	ds_read_b128 v[150:153], v250 offset:3072
	ds_read_b128 v[154:157], v251
	ds_read_b128 v[160:163], v251 offset:1024
	ds_read_b128 v[164:167], v251 offset:2048
	ds_read_b128 v[168:171], v251 offset:3072
	v_lshl_add_u64 v[216:217], s[0:1], 0, v[146:147]
	s_add_i32 m0, s46, 0xc000
	ds_read_b128 v[172:175], v159
	ds_read_b128 v[176:179], v159 offset:1024
	ds_read_b128 v[180:183], v159 offset:2048
	ds_read_b128 v[184:187], v159 offset:3072
	ds_read_b128 v[188:191], v159 offset:4096
	ds_read_b128 v[204:207], v159 offset:5120
	ds_read_b128 v[208:211], v159 offset:6144
	ds_read_b128 v[212:215], v159 offset:7168
	global_load_lds_dwordx4 v[216:217], off
	v_lshl_add_u64 v[216:217], s[0:1], 0, v[148:149]
	s_add_i32 m0, s46, 0xe000
	s_nop 0
	global_load_lds_dwordx4 v[216:217], off
	s_waitcnt vmcnt(8)
	s_waitcnt lgkmcnt(0)
	s_barrier
	s_setprio 1
	v_mfma_f32_16x16x32_bf16 v[120:123], v[128:131], v[172:175], v[120:123]
	v_mfma_f32_16x16x32_bf16 v[124:127], v[136:139], v[172:175], v[124:127]
	v_mfma_f32_16x16x32_bf16 v[116:119], v[128:131], v[180:183], v[116:119]
	v_mfma_f32_16x16x32_bf16 v[112:115], v[136:139], v[180:183], v[112:115]
	v_mfma_f32_16x16x32_bf16 v[108:111], v[128:131], v[188:191], v[108:111]
	v_mfma_f32_16x16x32_bf16 v[104:107], v[136:139], v[188:191], v[104:107]
	v_mfma_f32_16x16x32_bf16 v[100:103], v[128:131], v[208:211], v[100:103]
	v_mfma_f32_16x16x32_bf16 v[96:99], v[136:139], v[208:211], v[96:99]
	v_mfma_f32_16x16x32_bf16 v[120:123], v[132:135], v[176:179], v[120:123]
	v_mfma_f32_16x16x32_bf16 v[124:127], v[150:153], v[176:179], v[124:127]
	v_mfma_f32_16x16x32_bf16 v[116:119], v[132:135], v[184:187], v[116:119]
	v_mfma_f32_16x16x32_bf16 v[112:115], v[150:153], v[184:187], v[112:115]
	v_mfma_f32_16x16x32_bf16 v[108:111], v[132:135], v[204:207], v[108:111]
	v_mfma_f32_16x16x32_bf16 v[104:107], v[150:153], v[204:207], v[104:107]
	v_mfma_f32_16x16x32_bf16 v[100:103], v[132:135], v[212:215], v[100:103]
	v_mfma_f32_16x16x32_bf16 v[96:99], v[150:153], v[212:215], v[96:99]
	v_mfma_f32_16x16x32_bf16 v[60:63], v[154:157], v[172:175], v[60:63]
	v_mfma_f32_16x16x32_bf16 v[56:59], v[164:167], v[172:175], v[56:59]
	v_mfma_f32_16x16x32_bf16 v[52:55], v[154:157], v[180:183], v[52:55]
	v_mfma_f32_16x16x32_bf16 v[48:51], v[164:167], v[180:183], v[48:51]
	v_mfma_f32_16x16x32_bf16 v[44:47], v[154:157], v[188:191], v[44:47]
	v_mfma_f32_16x16x32_bf16 v[40:43], v[164:167], v[188:191], v[40:43]
	v_mfma_f32_16x16x32_bf16 v[36:39], v[154:157], v[208:211], v[36:39]
	v_mfma_f32_16x16x32_bf16 v[32:35], v[164:167], v[208:211], v[32:35]
	v_mfma_f32_16x16x32_bf16 v[60:63], v[160:163], v[176:179], v[60:63]
	v_mfma_f32_16x16x32_bf16 v[56:59], v[168:171], v[176:179], v[56:59]
	v_mfma_f32_16x16x32_bf16 v[52:55], v[160:163], v[184:187], v[52:55]
	v_mfma_f32_16x16x32_bf16 v[48:51], v[168:171], v[184:187], v[48:51]
	v_mfma_f32_16x16x32_bf16 v[44:47], v[160:163], v[204:207], v[44:47]
	v_mfma_f32_16x16x32_bf16 v[40:43], v[168:171], v[204:207], v[40:43]
	v_mfma_f32_16x16x32_bf16 v[36:39], v[160:163], v[212:215], v[36:39]
	v_mfma_f32_16x16x32_bf16 v[32:35], v[168:171], v[212:215], v[32:35]
	s_setprio 0
	s_barrier
	s_add_i32 s67, s67, s45
	v_lshl_add_u64 v[216:217], s[64:65], 0, v[192:193]
	s_mov_b32 m0, s67
	ds_read_b128 v[172:175], v159 offset:16384
	ds_read_b128 v[176:179], v159 offset:17408
	ds_read_b128 v[180:183], v159 offset:18432
	ds_read_b128 v[184:187], v159 offset:19456
	ds_read_b128 v[188:191], v159 offset:20480
	ds_read_b128 v[204:207], v159 offset:21504
	ds_read_b128 v[208:211], v159 offset:22528
	ds_read_b128 v[212:215], v159 offset:23552
	global_load_lds_dwordx4 v[216:217], off
	s_add_i32 m0, s67, 0x2000
	v_lshl_add_u64 v[218:219], s[64:65], 0, v[144:145]
	s_add_u32 s64, s64, s6
	s_addc_u32 s65, s65, s7
	s_add_i32 s63, s63, s45
	global_load_lds_dwordx4 v[218:219], off
	v_lshl_add_u64 v[220:221], s[64:65], 0, v[192:193]
	s_mov_b32 m0, s63
	v_lshl_add_u64 v[222:223], s[64:65], 0, v[144:145]
	global_load_lds_dwordx4 v[220:221], off
	s_add_i32 m0, s63, 0x2000
	v_lshl_add_u64 v[232:233], s[4:5], 0, v[140:141]
	global_load_lds_dwordx4 v[222:223], off
	s_mov_b32 m0, s46
	v_lshl_add_u64 v[234:235], s[4:5], 0, v[142:143]
	global_load_lds_dwordx4 v[232:233], off
	s_mov_b32 m0, s47
	s_nop 0
	global_load_lds_dwordx4 v[234:235], off
	s_waitcnt vmcnt(8)
	s_waitcnt lgkmcnt(0)
	s_barrier
; #define PG8_STAGE(bufoff, gbase, voff) do { _Pragma("unroll") for (int _i = 0; _i < 2; ++_i) \
;         __builtin_amdgcn_global_load_lds((const unsigned*)((const char*)(gbase) + (voff)[_i]), (LAS unsigned*)(lds + (bufoff) + ldsw + _i * 8192), 16, 0, 0); } while (0)
; #define PG8_LDA(dst, b, h) do { _Pragma("unroll") for (int m = 0; m < 4; ++m) _Pragma("unroll") for (int k = 0; k < 2; ++k) dst[m][k] = *(const LAS bf16x8*)(lds + PG8_SA(b, h) + aoff + m * 2048 + k * 1024); } while (0)
; #define PG8_LDB(dst, b, h) do { _Pragma("unroll") for (int n = 0; n < 2; ++n) _Pragma("unroll") for (int k = 0; k < 2; ++k) dst[n][k] = *(const LAS bf16x8*)(lds + PG8_SB(b, h) + boff + n * 2048 + k * 1024); } while (0)
; #define PG8_MMA(ai, bj, At, Bt) do { __builtin_amdgcn_s_setprio(1); _Pragma("unroll") for (int m = 0; m < 4; ++m) _Pragma("unroll") for (int n = 0; n < 2; ++n) _Pragma("unroll") for (int k = 0; k < 2; ++k) \
;         acc[ai][bj][m][n] = __builtin_amdgcn_mfma_f32_16x16x32_bf16(Bt[n][k], At[m][k], acc[ai][bj][m][n], 0, 0, 0); __builtin_amdgcn_s_setprio(0); } while (0)
; #define PG8_WAIT_V(n) asm volatile("s_waitcnt vmcnt(" #n ")" ::: "memory")
; #define PG8_WAIT_L(n) asm volatile("s_waitcnt lgkmcnt(" #n ")" ::: "memory")
; #define PG8_BAR __builtin_amdgcn_s_barrier()
; #define PG8_SCHED __builtin_amdgcn_sched_barrier(0)
; template <class EpiT, class Sched>
; __device__ __forceinline__ void gemm_phase(LAS unsigned char* lds, const Gemm g, const Sched& S, const EpiT& E, int wv) {
;     ...
;             PG8_WAIT_V(8); PG8_WAIT_L(0); PG8_BAR; PG8_MMA(1, 0, At, B0); PG8_MMA(1, 1, At, B1); PG8_BAR; PG8_SCHED;
;             PG8_LDB(B0, 1, 0); PG8_LDB(B1, 1, 1); PG8_SCHED; PG8_LDA(At, 1, 0); PG8_STAGE(PG8_SA(0, 1), a2 + hstepA, voffA);
;             PG8_WAIT_V(8); PG8_WAIT_L(0); PG8_BAR; PG8_MMA(0, 0, At, B0); PG8_MMA(0, 1, At, B1); PG8_BAR; PG8_SCHED;
	s_setprio 1
	v_mfma_f32_16x16x32_bf16 v[92:95], v[128:131], v[172:175], v[92:95]
	v_mfma_f32_16x16x32_bf16 v[88:91], v[136:139], v[172:175], v[88:91]
	v_mfma_f32_16x16x32_bf16 v[84:87], v[128:131], v[180:183], v[84:87]
	v_mfma_f32_16x16x32_bf16 v[80:83], v[136:139], v[180:183], v[80:83]
	v_mfma_f32_16x16x32_bf16 v[76:79], v[128:131], v[188:191], v[76:79]
	v_mfma_f32_16x16x32_bf16 v[72:75], v[136:139], v[188:191], v[72:75]
	v_mfma_f32_16x16x32_bf16 v[68:71], v[128:131], v[208:211], v[68:71]
	v_mfma_f32_16x16x32_bf16 v[64:67], v[136:139], v[208:211], v[64:67]
	v_mfma_f32_16x16x32_bf16 v[92:95], v[132:135], v[176:179], v[92:95]
	v_mfma_f32_16x16x32_bf16 v[88:91], v[150:153], v[176:179], v[88:91]
	v_mfma_f32_16x16x32_bf16 v[84:87], v[132:135], v[184:187], v[84:87]
	v_mfma_f32_16x16x32_bf16 v[80:83], v[150:153], v[184:187], v[80:83]
	v_mfma_f32_16x16x32_bf16 v[76:79], v[132:135], v[204:207], v[76:79]
	v_mfma_f32_16x16x32_bf16 v[72:75], v[150:153], v[204:207], v[72:75]
	v_mfma_f32_16x16x32_bf16 v[68:71], v[132:135], v[212:215], v[68:71]
	v_mfma_f32_16x16x32_bf16 v[64:67], v[150:153], v[212:215], v[64:67]
	v_mfma_f32_16x16x32_bf16 v[28:31], v[154:157], v[172:175], v[28:31]
	v_mfma_f32_16x16x32_bf16 v[24:27], v[164:167], v[172:175], v[24:27]
	v_mfma_f32_16x16x32_bf16 v[20:23], v[154:157], v[180:183], v[20:23]
	v_mfma_f32_16x16x32_bf16 v[16:19], v[164:167], v[180:183], v[16:19]
	v_mfma_f32_16x16x32_bf16 v[12:15], v[154:157], v[188:191], v[12:15]
	v_mfma_f32_16x16x32_bf16 v[8:11], v[164:167], v[188:191], v[8:11]
	v_mfma_f32_16x16x32_bf16 v[4:7], v[154:157], v[208:211], v[4:7]
	v_mfma_f32_16x16x32_bf16 v[0:3], v[164:167], v[208:211], v[0:3]
	v_mfma_f32_16x16x32_bf16 v[28:31], v[160:163], v[176:179], v[28:31]
	v_mfma_f32_16x16x32_bf16 v[24:27], v[168:171], v[176:179], v[24:27]
	v_mfma_f32_16x16x32_bf16 v[20:23], v[160:163], v[184:187], v[20:23]
	v_mfma_f32_16x16x32_bf16 v[16:19], v[168:171], v[184:187], v[16:19]
	v_mfma_f32_16x16x32_bf16 v[12:15], v[160:163], v[204:207], v[12:15]
	v_mfma_f32_16x16x32_bf16 v[8:11], v[168:171], v[204:207], v[8:11]
	v_mfma_f32_16x16x32_bf16 v[4:7], v[160:163], v[212:215], v[4:7]
	v_mfma_f32_16x16x32_bf16 v[0:3], v[168:171], v[212:215], v[0:3]
	s_setprio 0
	s_barrier
	s_add_i32 s63, 0, 0x18000
	s_add_i32 s64, 0, 0x1c000
	ds_read_b128 v[128:131], v252
	ds_read_b128 v[132:135], v252 offset:1024
	ds_read_b128 v[136:139], v252 offset:2048
	ds_read_b128 v[150:153], v252 offset:3072
	ds_read_b128 v[154:157], v253
	ds_read_b128 v[160:163], v253 offset:1024
	ds_read_b128 v[164:167], v253 offset:2048
	ds_read_b128 v[168:171], v253 offset:3072
	s_add_u32 s4, s4, s6
	s_addc_u32 s5, s5, s7
	s_mov_b32 m0, s48
	v_lshl_add_u64 v[240:241], s[4:5], 0, v[140:141]
	ds_read_b128 v[172:175], v159 offset:32768
	ds_read_b128 v[176:179], v159 offset:33792
	ds_read_b128 v[180:183], v159 offset:34816
	ds_read_b128 v[184:187], v159 offset:35840
	ds_read_b128 v[188:191], v159 offset:36864
	ds_read_b128 v[204:207], v159 offset:37888
	ds_read_b128 v[208:211], v159 offset:38912
	ds_read_b128 v[212:215], v159 offset:39936
	global_load_lds_dwordx4 v[240:241], off
	v_lshl_add_u64 v[240:241], s[4:5], 0, v[142:143]
	s_mov_b32 m0, s49
	s_nop 0
	global_load_lds_dwordx4 v[240:241], off
	s_waitcnt vmcnt(8)
	s_waitcnt lgkmcnt(0)
	s_barrier
	s_setprio 1
	v_mfma_f32_16x16x32_bf16 v[120:123], v[128:131], v[172:175], v[120:123]
	v_mfma_f32_16x16x32_bf16 v[124:127], v[136:139], v[172:175], v[124:127]
	v_mfma_f32_16x16x32_bf16 v[116:119], v[128:131], v[180:183], v[116:119]
	v_mfma_f32_16x16x32_bf16 v[112:115], v[136:139], v[180:183], v[112:115]
	v_mfma_f32_16x16x32_bf16 v[108:111], v[128:131], v[188:191], v[108:111]
	v_mfma_f32_16x16x32_bf16 v[104:107], v[136:139], v[188:191], v[104:107]
	v_mfma_f32_16x16x32_bf16 v[100:103], v[128:131], v[208:211], v[100:103]
	v_mfma_f32_16x16x32_bf16 v[96:99], v[136:139], v[208:211], v[96:99]
	v_mfma_f32_16x16x32_bf16 v[120:123], v[132:135], v[176:179], v[120:123]
	v_mfma_f32_16x16x32_bf16 v[124:127], v[150:153], v[176:179], v[124:127]
	v_mfma_f32_16x16x32_bf16 v[116:119], v[132:135], v[184:187], v[116:119]
	v_mfma_f32_16x16x32_bf16 v[112:115], v[150:153], v[184:187], v[112:115]
	v_mfma_f32_16x16x32_bf16 v[108:111], v[132:135], v[204:207], v[108:111]
	v_mfma_f32_16x16x32_bf16 v[104:107], v[150:153], v[204:207], v[104:107]
	v_mfma_f32_16x16x32_bf16 v[100:103], v[132:135], v[212:215], v[100:103]
	v_mfma_f32_16x16x32_bf16 v[96:99], v[150:153], v[212:215], v[96:99]
	v_mfma_f32_16x16x32_bf16 v[60:63], v[154:157], v[172:175], v[60:63]
	v_mfma_f32_16x16x32_bf16 v[56:59], v[164:167], v[172:175], v[56:59]
	v_mfma_f32_16x16x32_bf16 v[52:55], v[154:157], v[180:183], v[52:55]
	v_mfma_f32_16x16x32_bf16 v[48:51], v[164:167], v[180:183], v[48:51]
	v_mfma_f32_16x16x32_bf16 v[44:47], v[154:157], v[188:191], v[44:47]
	v_mfma_f32_16x16x32_bf16 v[40:43], v[164:167], v[188:191], v[40:43]
	v_mfma_f32_16x16x32_bf16 v[36:39], v[154:157], v[208:211], v[36:39]
	v_mfma_f32_16x16x32_bf16 v[32:35], v[164:167], v[208:211], v[32:35]
	v_mfma_f32_16x16x32_bf16 v[60:63], v[160:163], v[176:179], v[60:63]
	v_mfma_f32_16x16x32_bf16 v[56:59], v[168:171], v[176:179], v[56:59]
	v_mfma_f32_16x16x32_bf16 v[52:55], v[160:163], v[184:187], v[52:55]
	v_mfma_f32_16x16x32_bf16 v[48:51], v[168:171], v[184:187], v[48:51]
	v_mfma_f32_16x16x32_bf16 v[44:47], v[160:163], v[204:207], v[44:47]
	v_mfma_f32_16x16x32_bf16 v[40:43], v[168:171], v[204:207], v[40:43]
	v_mfma_f32_16x16x32_bf16 v[36:39], v[160:163], v[212:215], v[36:39]
	v_mfma_f32_16x16x32_bf16 v[32:35], v[168:171], v[212:215], v[32:35]
	s_setprio 0
	s_barrier
; #define PG8_STAGE(bufoff, gbase, voff) do { _Pragma("unroll") for (int _i = 0; _i < 2; ++_i) \
;         __builtin_amdgcn_global_load_lds((const unsigned*)((const char*)(gbase) + (voff)[_i]), (LAS unsigned*)(lds + (bufoff) + ldsw + _i * 8192), 16, 0, 0); } while (0)
; #define PG8_LDA(dst, b, h) do { _Pragma("unroll") for (int m = 0; m < 4; ++m) _Pragma("unroll") for (int k = 0; k < 2; ++k) dst[m][k] = *(const LAS bf16x8*)(lds + PG8_SA(b, h) + aoff + m * 2048 + k * 1024); } while (0)
; #define PG8_MMA(ai, bj, At, Bt) do { __builtin_amdgcn_s_setprio(1); _Pragma("unroll") for (int m = 0; m < 4; ++m) _Pragma("unroll") for (int n = 0; n < 2; ++n) _Pragma("unroll") for (int k = 0; k < 2; ++k) \
;         acc[ai][bj][m][n] = __builtin_amdgcn_mfma_f32_16x16x32_bf16(Bt[n][k], At[m][k], acc[ai][bj][m][n], 0, 0, 0); __builtin_amdgcn_s_setprio(0); } while (0)
; #define PG8_WAIT_V(n) asm volatile("s_waitcnt vmcnt(" #n ")" ::: "memory")
; #define PG8_WAIT_L(n) asm volatile("s_waitcnt lgkmcnt(" #n ")" ::: "memory")
; #define PG8_BAR __builtin_amdgcn_s_barrier()
; #define PG8_SCHED __builtin_amdgcn_sched_barrier(0)
; template <class EpiT, class Sched>
; __device__ __forceinline__ void gemm_phase(LAS unsigned char* lds, const Gemm g, const Sched& S, const EpiT& E, int wv) {
;     ...
;             PG8_LDA(At, 1, 1); PG8_STAGE(PG8_SB(1, 0), b3, voffB); PG8_STAGE(PG8_SB(1, 1), b3 + hstepB, voffB); PG8_STAGE(PG8_SA(1, 0), a3, voffA);
;             PG8_WAIT_V(8); PG8_WAIT_L(0); PG8_BAR; PG8_MMA(1, 0, At, B0); PG8_MMA(1, 1, At, B1); PG8_BAR; PG8_SCHED;
;         }
	s_add_i32 s4, s63, s45
	v_lshl_add_u64 v[216:217], v[216:217], 0, s[92:93]
	s_mov_b32 m0, s4
	ds_read_b128 v[172:175], v159 offset:49152
	ds_read_b128 v[176:179], v159 offset:50176
	ds_read_b128 v[180:183], v159 offset:51200
	ds_read_b128 v[184:187], v159 offset:52224
	ds_read_b128 v[188:191], v159 offset:53248
	ds_read_b128 v[204:207], v159 offset:54272
	ds_read_b128 v[208:211], v159 offset:55296
	ds_read_b128 v[212:215], v159 offset:56320
	global_load_lds_dwordx4 v[216:217], off
	v_lshl_add_u64 v[216:217], v[218:219], 0, s[92:93]
	s_add_i32 m0, s4, 0x2000
	s_add_i32 s4, s64, s45
	global_load_lds_dwordx4 v[216:217], off
	v_lshl_add_u64 v[216:217], v[220:221], 0, s[92:93]
	s_mov_b32 m0, s4
	s_nop 0
	global_load_lds_dwordx4 v[216:217], off
	v_lshl_add_u64 v[216:217], v[222:223], 0, s[92:93]
	s_add_i32 m0, s4, 0x2000
	s_nop 0
	global_load_lds_dwordx4 v[216:217], off
	v_lshl_add_u64 v[216:217], v[232:233], 0, s[92:93]
	s_mov_b32 m0, s50
	s_nop 0
	global_load_lds_dwordx4 v[216:217], off
	v_lshl_add_u64 v[216:217], v[234:235], 0, s[92:93]
	s_mov_b32 m0, s51
	s_nop 0
	global_load_lds_dwordx4 v[216:217], off
	s_waitcnt vmcnt(8)
	s_waitcnt lgkmcnt(0)
	s_barrier
	s_setprio 1
	v_mfma_f32_16x16x32_bf16 v[92:95], v[128:131], v[172:175], v[92:95]
	v_mfma_f32_16x16x32_bf16 v[88:91], v[136:139], v[172:175], v[88:91]
	v_mfma_f32_16x16x32_bf16 v[84:87], v[128:131], v[180:183], v[84:87]
	v_mfma_f32_16x16x32_bf16 v[80:83], v[136:139], v[180:183], v[80:83]
	v_mfma_f32_16x16x32_bf16 v[76:79], v[128:131], v[188:191], v[76:79]
	v_mfma_f32_16x16x32_bf16 v[72:75], v[136:139], v[188:191], v[72:75]
	v_mfma_f32_16x16x32_bf16 v[68:71], v[128:131], v[208:211], v[68:71]
	v_mfma_f32_16x16x32_bf16 v[64:67], v[136:139], v[208:211], v[64:67]
	v_mfma_f32_16x16x32_bf16 v[92:95], v[132:135], v[176:179], v[92:95]
	v_mfma_f32_16x16x32_bf16 v[88:91], v[150:153], v[176:179], v[88:91]
	v_mfma_f32_16x16x32_bf16 v[84:87], v[132:135], v[184:187], v[84:87]
	v_mfma_f32_16x16x32_bf16 v[80:83], v[150:153], v[184:187], v[80:83]
	v_mfma_f32_16x16x32_bf16 v[76:79], v[132:135], v[204:207], v[76:79]
	v_mfma_f32_16x16x32_bf16 v[72:75], v[150:153], v[204:207], v[72:75]
	v_mfma_f32_16x16x32_bf16 v[68:71], v[132:135], v[212:215], v[68:71]
	v_mfma_f32_16x16x32_bf16 v[64:67], v[150:153], v[212:215], v[64:67]
	v_mfma_f32_16x16x32_bf16 v[28:31], v[154:157], v[172:175], v[28:31]
	v_mfma_f32_16x16x32_bf16 v[24:27], v[164:167], v[172:175], v[24:27]
	v_mfma_f32_16x16x32_bf16 v[20:23], v[154:157], v[180:183], v[20:23]
	v_mfma_f32_16x16x32_bf16 v[16:19], v[164:167], v[180:183], v[16:19]
	v_mfma_f32_16x16x32_bf16 v[12:15], v[154:157], v[188:191], v[12:15]
	v_mfma_f32_16x16x32_bf16 v[8:11], v[164:167], v[188:191], v[8:11]
	v_mfma_f32_16x16x32_bf16 v[4:7], v[154:157], v[208:211], v[4:7]
	v_mfma_f32_16x16x32_bf16 v[0:3], v[164:167], v[208:211], v[0:3]
	v_mfma_f32_16x16x32_bf16 v[28:31], v[160:163], v[176:179], v[28:31]
	v_mfma_f32_16x16x32_bf16 v[24:27], v[168:171], v[176:179], v[24:27]
	v_mfma_f32_16x16x32_bf16 v[20:23], v[160:163], v[184:187], v[20:23]
	v_mfma_f32_16x16x32_bf16 v[16:19], v[168:171], v[184:187], v[16:19]
	v_mfma_f32_16x16x32_bf16 v[12:15], v[160:163], v[204:207], v[12:15]
	v_mfma_f32_16x16x32_bf16 v[8:11], v[168:171], v[204:207], v[8:11]
	v_mfma_f32_16x16x32_bf16 v[4:7], v[160:163], v[212:215], v[4:7]
	v_mfma_f32_16x16x32_bf16 v[0:3], v[168:171], v[212:215], v[0:3]
	s_setprio 0
	s_barrier
	s_add_u32 s0, s0, 0x100
	s_addc_u32 s1, s1, 0
	s_add_u32 s36, s36, 0x100
	s_addc_u32 s37, s37, 0
	s_cmp_ge_i32 s39, s52
	s_mov_b32 s4, s39
	s_cbranch_scc0 .LBB0_623
	v_readlane_b32 s67, v255, 5

; #define PG8_STAGE(bufoff, gbase, voff) do { _Pragma("unroll") for (int _i = 0; _i < 2; ++_i) \
;         __builtin_amdgcn_global_load_lds((const unsigned*)((const char*)(gbase) + (voff)[_i]), (LAS unsigned*)(lds + (bufoff) + ldsw + _i * 8192), 16, 0, 0); } while (0)
; #define PG8_LDA(dst, b, h) do { _Pragma("unroll") for (int m = 0; m < 4; ++m) _Pragma("unroll") for (int k = 0; k < 2; ++k) dst[m][k] = *(const LAS bf16x8*)(lds + PG8_SA(b, h) + aoff + m * 2048 + k * 1024); } while (0)
; #define PG8_LDB(dst, b, h) do { _Pragma("unroll") for (int n = 0; n < 2; ++n) _Pragma("unroll") for (int k = 0; k < 2; ++k) dst[n][k] = *(const LAS bf16x8*)(lds + PG8_SB(b, h) + boff + n * 2048 + k * 1024); } while (0)
; #define PG8_MMA(ai, bj, At, Bt) do { __builtin_amdgcn_s_setprio(1); _Pragma("unroll") for (int m = 0; m < 4; ++m) _Pragma("unroll") for (int n = 0; n < 2; ++n) _Pragma("unroll") for (int k = 0; k < 2; ++k) \
;         acc[ai][bj][m][n] = __builtin_amdgcn_mfma_f32_16x16x32_bf16(Bt[n][k], At[m][k], acc[ai][bj][m][n], 0, 0, 0); __builtin_amdgcn_s_setprio(0); } while (0)
; #define PG8_WAIT_V(n) asm volatile("s_waitcnt vmcnt(" #n ")" ::: "memory")
; #define PG8_WAIT_L(n) asm volatile("s_waitcnt lgkmcnt(" #n ")" ::: "memory")
; #define PG8_BAR __builtin_amdgcn_s_barrier()
; #define PG8_SCHED __builtin_amdgcn_sched_barrier(0)
; template <class EpiT, class Sched>
; __device__ __forceinline__ void gemm_phase(LAS unsigned char* lds, const Gemm g, const Sched& S, const EpiT& E, int wv) {
;     ...
;             const bool last = (t == nt - 2);
;             const char* a1 = cA + (size_t)(t + 1) * kstep;
;             const char* a2 = last ? nA : cA + (size_t)(t + 2) * kstep; const char* b2 = last ? nB : cB + (size_t)(t + 2) * kstep;
;             const char* a3 = a2 + kstep; const char* b3 = b2 + kstep;
;             PG8_LDB(B0, 0, 0); PG8_LDB(B1, 0, 1); PG8_SCHED; PG8_LDA(At, 0, 0); PG8_STAGE(PG8_SA(1, 1), a1 + hstepA, voffA);
;             PG8_WAIT_V(8); PG8_WAIT_L(0); PG8_BAR; PG8_MMA(0, 0, At, B0); PG8_MMA(0, 1, At, B1); PG8_BAR; PG8_SCHED;
;             PG8_LDA(At, 0, 1); PG8_STAGE(PG8_SB(0, 0), b2, voffB); PG8_STAGE(PG8_SB(0, 1), b2 + hstepB, voffB); PG8_STAGE(PG8_SA(0, 0), a2, voffA);
;             PG8_WAIT_V(8); PG8_WAIT_L(0); PG8_BAR; PG8_MMA(1, 0, At, B0); PG8_MMA(1, 1, At, B1); PG8_BAR; PG8_SCHED;
.LBB0_1042:
	s_add_u32 s24, s22, 0xfff80080
	s_addc_u32 s25, s23, -1
	s_add_i32 s56, 0, 0x10000
	s_cmp_eq_u32 s55, 4
	s_cselect_b32 s27, s1, s25
	s_cselect_b32 s26, s15, s24
	s_cselect_b32 s25, s13, s54
	s_cselect_b32 s24, s33, s53
	s_add_i32 s58, 0, 0x14000
	ds_read_b128 v[128:131], v250
	ds_read_b128 v[132:135], v250 offset:1024
	ds_read_b128 v[136:139], v250 offset:2048
	ds_read_b128 v[140:143], v250 offset:3072
	ds_read_b128 v[144:147], v251
	ds_read_b128 v[148:151], v251 offset:1024
	ds_read_b128 v[152:155], v251 offset:2048
	ds_read_b128 v[166:169], v251 offset:3072
	s_add_i32 m0, s21, 0xc000
	ds_read_b128 v[170:173], v213
	ds_read_b128 v[174:177], v213 offset:1024
	ds_read_b128 v[178:181], v213 offset:2048
	ds_read_b128 v[182:185], v213 offset:3072
	ds_read_b128 v[186:189], v213 offset:4096
	ds_read_b128 v[204:207], v213 offset:5120
	ds_read_b128 v[208:211], v213 offset:6144
	ds_read_b128 v[214:217], v213 offset:7168
	global_load_lds_dwordx4 v162, s[22:23]
	s_add_i32 m0, s21, 0xe000
	s_nop 0
	global_load_lds_dwordx4 v164, s[22:23]
	s_waitcnt vmcnt(8)
	s_waitcnt lgkmcnt(0)
	s_barrier
	s_setprio 1
	v_mfma_f32_16x16x32_bf16 v[124:127], v[128:131], v[170:173], v[124:127]
	v_mfma_f32_16x16x32_bf16 v[120:123], v[136:139], v[170:173], v[120:123]
	v_mfma_f32_16x16x32_bf16 v[116:119], v[128:131], v[178:181], v[116:119]
	v_mfma_f32_16x16x32_bf16 v[112:115], v[136:139], v[178:181], v[112:115]
	v_mfma_f32_16x16x32_bf16 v[108:111], v[128:131], v[186:189], v[108:111]
	v_mfma_f32_16x16x32_bf16 v[104:107], v[136:139], v[186:189], v[104:107]
	v_mfma_f32_16x16x32_bf16 v[100:103], v[128:131], v[208:211], v[100:103]
	v_mfma_f32_16x16x32_bf16 v[96:99], v[136:139], v[208:211], v[96:99]
	v_mfma_f32_16x16x32_bf16 v[124:127], v[132:135], v[174:177], v[124:127]
	v_mfma_f32_16x16x32_bf16 v[120:123], v[140:143], v[174:177], v[120:123]
	v_mfma_f32_16x16x32_bf16 v[116:119], v[132:135], v[182:185], v[116:119]
	v_mfma_f32_16x16x32_bf16 v[112:115], v[140:143], v[182:185], v[112:115]
	v_mfma_f32_16x16x32_bf16 v[108:111], v[132:135], v[204:207], v[108:111]
	v_mfma_f32_16x16x32_bf16 v[104:107], v[140:143], v[204:207], v[104:107]
	v_mfma_f32_16x16x32_bf16 v[100:103], v[132:135], v[214:217], v[100:103]
	v_mfma_f32_16x16x32_bf16 v[96:99], v[140:143], v[214:217], v[96:99]
	v_mfma_f32_16x16x32_bf16 v[60:63], v[144:147], v[170:173], v[60:63]
	v_mfma_f32_16x16x32_bf16 v[56:59], v[152:155], v[170:173], v[56:59]
	v_mfma_f32_16x16x32_bf16 v[52:55], v[144:147], v[178:181], v[52:55]
	v_mfma_f32_16x16x32_bf16 v[48:51], v[152:155], v[178:181], v[48:51]
	v_mfma_f32_16x16x32_bf16 v[44:47], v[144:147], v[186:189], v[44:47]
	v_mfma_f32_16x16x32_bf16 v[40:43], v[152:155], v[186:189], v[40:43]
	v_mfma_f32_16x16x32_bf16 v[36:39], v[144:147], v[208:211], v[36:39]
	v_mfma_f32_16x16x32_bf16 v[32:35], v[152:155], v[208:211], v[32:35]
	v_mfma_f32_16x16x32_bf16 v[60:63], v[148:151], v[174:177], v[60:63]
	v_mfma_f32_16x16x32_bf16 v[56:59], v[166:169], v[174:177], v[56:59]
	v_mfma_f32_16x16x32_bf16 v[52:55], v[148:151], v[182:185], v[52:55]
	v_mfma_f32_16x16x32_bf16 v[48:51], v[166:169], v[182:185], v[48:51]
	v_mfma_f32_16x16x32_bf16 v[44:47], v[148:151], v[204:207], v[44:47]
	v_mfma_f32_16x16x32_bf16 v[40:43], v[166:169], v[204:207], v[40:43]
	v_mfma_f32_16x16x32_bf16 v[36:39], v[148:151], v[214:217], v[36:39]
	v_mfma_f32_16x16x32_bf16 v[32:35], v[166:169], v[214:217], v[32:35]
	s_setprio 0
	s_barrier
	s_add_i32 s56, s56, s39
	s_add_u32 s62, s24, s92
	s_addc_u32 s63, s25, s93
	s_mov_b32 m0, s56
	ds_read_b128 v[170:173], v213 offset:16384
	ds_read_b128 v[174:177], v213 offset:17408
	ds_read_b128 v[178:181], v213 offset:18432
	ds_read_b128 v[182:185], v213 offset:19456
	ds_read_b128 v[186:189], v213 offset:20480
	ds_read_b128 v[204:207], v213 offset:21504
	ds_read_b128 v[208:211], v213 offset:22528
	ds_read_b128 v[214:217], v213 offset:23552
	global_load_lds_dwordx4 v192, s[24:25]
	s_add_i32 m0, s56, 0x2000
	s_add_u32 s56, s24, 0x20000
	s_addc_u32 s57, s25, 0
	s_add_i32 s58, s58, s39
	global_load_lds_dwordx4 v156, s[24:25]
	s_mov_b32 m0, s58
	s_nop 0
	global_load_lds_dwordx4 v192, s[56:57]
	s_add_i32 m0, s58, 0x2000
	s_nop 0
	global_load_lds_dwordx4 v156, s[56:57]
	s_add_u32 s64, s26, s92
	s_addc_u32 s65, s27, s93
	s_mov_b32 m0, s21
	s_nop 0
	global_load_lds_dwordx4 v160, s[26:27]
	s_mov_b32 m0, s45
	s_nop 0
	global_load_lds_dwordx4 v158, s[26:27]
	s_waitcnt vmcnt(8)
	s_waitcnt lgkmcnt(0)
	s_barrier
	s_setprio 1
	v_mfma_f32_16x16x32_bf16 v[92:95], v[128:131], v[170:173], v[92:95]
	v_mfma_f32_16x16x32_bf16 v[88:91], v[136:139], v[170:173], v[88:91]
	v_mfma_f32_16x16x32_bf16 v[84:87], v[128:131], v[178:181], v[84:87]
	v_mfma_f32_16x16x32_bf16 v[80:83], v[136:139], v[178:181], v[80:83]
	v_mfma_f32_16x16x32_bf16 v[76:79], v[128:131], v[186:189], v[76:79]
	v_mfma_f32_16x16x32_bf16 v[72:75], v[136:139], v[186:189], v[72:75]
	v_mfma_f32_16x16x32_bf16 v[68:71], v[128:131], v[208:211], v[68:71]
	v_mfma_f32_16x16x32_bf16 v[64:67], v[136:139], v[208:211], v[64:67]
	v_mfma_f32_16x16x32_bf16 v[92:95], v[132:135], v[174:177], v[92:95]
	v_mfma_f32_16x16x32_bf16 v[88:91], v[140:143], v[174:177], v[88:91]
	v_mfma_f32_16x16x32_bf16 v[84:87], v[132:135], v[182:185], v[84:87]
	v_mfma_f32_16x16x32_bf16 v[80:83], v[140:143], v[182:185], v[80:83]
	v_mfma_f32_16x16x32_bf16 v[76:79], v[132:135], v[204:207], v[76:79]
	v_mfma_f32_16x16x32_bf16 v[72:75], v[140:143], v[204:207], v[72:75]
	v_mfma_f32_16x16x32_bf16 v[68:71], v[132:135], v[214:217], v[68:71]
	v_mfma_f32_16x16x32_bf16 v[64:67], v[140:143], v[214:217], v[64:67]
	v_mfma_f32_16x16x32_bf16 v[28:31], v[144:147], v[170:173], v[28:31]
	v_mfma_f32_16x16x32_bf16 v[24:27], v[152:155], v[170:173], v[24:27]
	v_mfma_f32_16x16x32_bf16 v[20:23], v[144:147], v[178:181], v[20:23]
	v_mfma_f32_16x16x32_bf16 v[16:19], v[152:155], v[178:181], v[16:19]
	v_mfma_f32_16x16x32_bf16 v[12:15], v[144:147], v[186:189], v[12:15]
	v_mfma_f32_16x16x32_bf16 v[8:11], v[152:155], v[186:189], v[8:11]
	v_mfma_f32_16x16x32_bf16 v[4:7], v[144:147], v[208:211], v[4:7]
	v_mfma_f32_16x16x32_bf16 v[0:3], v[152:155], v[208:211], v[0:3]
	v_mfma_f32_16x16x32_bf16 v[28:31], v[148:151], v[174:177], v[28:31]
	v_mfma_f32_16x16x32_bf16 v[24:27], v[166:169], v[174:177], v[24:27]
	v_mfma_f32_16x16x32_bf16 v[20:23], v[148:151], v[182:185], v[20:23]
	v_mfma_f32_16x16x32_bf16 v[16:19], v[166:169], v[182:185], v[16:19]
	v_mfma_f32_16x16x32_bf16 v[12:15], v[148:151], v[204:207], v[12:15]
	v_mfma_f32_16x16x32_bf16 v[8:11], v[166:169], v[204:207], v[8:11]
	v_mfma_f32_16x16x32_bf16 v[4:7], v[148:151], v[214:217], v[4:7]
	v_mfma_f32_16x16x32_bf16 v[0:3], v[166:169], v[214:217], v[0:3]
	s_setprio 0
	s_barrier
; #define PG8_STAGE(bufoff, gbase, voff) do { _Pragma("unroll") for (int _i = 0; _i < 2; ++_i) \
;         __builtin_amdgcn_global_load_lds((const unsigned*)((const char*)(gbase) + (voff)[_i]), (LAS unsigned*)(lds + (bufoff) + ldsw + _i * 8192), 16, 0, 0); } while (0)
; #define PG8_LDA(dst, b, h) do { _Pragma("unroll") for (int m = 0; m < 4; ++m) _Pragma("unroll") for (int k = 0; k < 2; ++k) dst[m][k] = *(const LAS bf16x8*)(lds + PG8_SA(b, h) + aoff + m * 2048 + k * 1024); } while (0)
; #define PG8_LDB(dst, b, h) do { _Pragma("unroll") for (int n = 0; n < 2; ++n) _Pragma("unroll") for (int k = 0; k < 2; ++k) dst[n][k] = *(const LAS bf16x8*)(lds + PG8_SB(b, h) + boff + n * 2048 + k * 1024); } while (0)
; #define PG8_MMA(ai, bj, At, Bt) do { __builtin_amdgcn_s_setprio(1); _Pragma("unroll") for (int m = 0; m < 4; ++m) _Pragma("unroll") for (int n = 0; n < 2; ++n) _Pragma("unroll") for (int k = 0; k < 2; ++k) \
;         acc[ai][bj][m][n] = __builtin_amdgcn_mfma_f32_16x16x32_bf16(Bt[n][k], At[m][k], acc[ai][bj][m][n], 0, 0, 0); __builtin_amdgcn_s_setprio(0); } while (0)
; #define PG8_WAIT_V(n) asm volatile("s_waitcnt vmcnt(" #n ")" ::: "memory")
; #define PG8_WAIT_L(n) asm volatile("s_waitcnt lgkmcnt(" #n ")" ::: "memory")
; #define PG8_BAR __builtin_amdgcn_s_barrier()
; #define PG8_SCHED __builtin_amdgcn_sched_barrier(0)
; template <class EpiT, class Sched>
; __device__ __forceinline__ void gemm_phase(LAS unsigned char* lds, const Gemm g, const Sched& S, const EpiT& E, int wv) {
;     ...
;             PG8_LDB(B0, 1, 0); PG8_LDB(B1, 1, 1); PG8_SCHED; PG8_LDA(At, 1, 0); PG8_STAGE(PG8_SA(0, 1), a2 + hstepA, voffA);
;             PG8_WAIT_V(8); PG8_WAIT_L(0); PG8_BAR; PG8_MMA(0, 0, At, B0); PG8_MMA(0, 1, At, B1); PG8_BAR; PG8_SCHED;
;             PG8_LDA(At, 1, 1); PG8_STAGE(PG8_SB(1, 0), b3, voffB); PG8_STAGE(PG8_SB(1, 1), b3 + hstepB, voffB); PG8_STAGE(PG8_SA(1, 0), a3, voffA);
;             PG8_WAIT_V(8); PG8_WAIT_L(0); PG8_BAR; PG8_MMA(1, 0, At, B0); PG8_MMA(1, 1, At, B1); PG8_BAR; PG8_SCHED;
;         }
;         if (wr == 0) PG8_BAR;
	s_add_i32 s56, 0, 0x18000
	s_add_i32 s57, 0, 0x1c000
	ds_read_b128 v[128:131], v252
	ds_read_b128 v[132:135], v252 offset:1024
	ds_read_b128 v[136:139], v252 offset:2048
	ds_read_b128 v[140:143], v252 offset:3072
	ds_read_b128 v[144:147], v253
	ds_read_b128 v[148:151], v253 offset:1024
	ds_read_b128 v[152:155], v253 offset:2048
	ds_read_b128 v[166:169], v253 offset:3072
	s_add_u32 s26, s26, 0x80000
	s_addc_u32 s27, s27, 0
	s_mov_b32 m0, s46
	ds_read_b128 v[170:173], v213 offset:32768
	ds_read_b128 v[174:177], v213 offset:33792
	ds_read_b128 v[178:181], v213 offset:34816
	ds_read_b128 v[182:185], v213 offset:35840
	ds_read_b128 v[186:189], v213 offset:36864
	ds_read_b128 v[204:207], v213 offset:37888
	ds_read_b128 v[208:211], v213 offset:38912
	ds_read_b128 v[214:217], v213 offset:39936
	global_load_lds_dwordx4 v160, s[26:27]
	s_mov_b32 m0, s47
	s_nop 0
	global_load_lds_dwordx4 v158, s[26:27]
	s_waitcnt vmcnt(8)
	s_waitcnt lgkmcnt(0)
	s_barrier
	s_setprio 1
	v_mfma_f32_16x16x32_bf16 v[124:127], v[128:131], v[170:173], v[124:127]
	v_mfma_f32_16x16x32_bf16 v[120:123], v[136:139], v[170:173], v[120:123]
	v_mfma_f32_16x16x32_bf16 v[116:119], v[128:131], v[178:181], v[116:119]
	v_mfma_f32_16x16x32_bf16 v[112:115], v[136:139], v[178:181], v[112:115]
	v_mfma_f32_16x16x32_bf16 v[108:111], v[128:131], v[186:189], v[108:111]
	v_mfma_f32_16x16x32_bf16 v[104:107], v[136:139], v[186:189], v[104:107]
	v_mfma_f32_16x16x32_bf16 v[100:103], v[128:131], v[208:211], v[100:103]
	v_mfma_f32_16x16x32_bf16 v[96:99], v[136:139], v[208:211], v[96:99]
	v_mfma_f32_16x16x32_bf16 v[124:127], v[132:135], v[174:177], v[124:127]
	v_mfma_f32_16x16x32_bf16 v[120:123], v[140:143], v[174:177], v[120:123]
	v_mfma_f32_16x16x32_bf16 v[116:119], v[132:135], v[182:185], v[116:119]
	v_mfma_f32_16x16x32_bf16 v[112:115], v[140:143], v[182:185], v[112:115]
	v_mfma_f32_16x16x32_bf16 v[108:111], v[132:135], v[204:207], v[108:111]
	v_mfma_f32_16x16x32_bf16 v[104:107], v[140:143], v[204:207], v[104:107]
	v_mfma_f32_16x16x32_bf16 v[100:103], v[132:135], v[214:217], v[100:103]
	v_mfma_f32_16x16x32_bf16 v[96:99], v[140:143], v[214:217], v[96:99]
	v_mfma_f32_16x16x32_bf16 v[60:63], v[144:147], v[170:173], v[60:63]
	v_mfma_f32_16x16x32_bf16 v[56:59], v[152:155], v[170:173], v[56:59]
	v_mfma_f32_16x16x32_bf16 v[52:55], v[144:147], v[178:181], v[52:55]
	v_mfma_f32_16x16x32_bf16 v[48:51], v[152:155], v[178:181], v[48:51]
	v_mfma_f32_16x16x32_bf16 v[44:47], v[144:147], v[186:189], v[44:47]
	v_mfma_f32_16x16x32_bf16 v[40:43], v[152:155], v[186:189], v[40:43]
	v_mfma_f32_16x16x32_bf16 v[36:39], v[144:147], v[208:211], v[36:39]
	v_mfma_f32_16x16x32_bf16 v[32:35], v[152:155], v[208:211], v[32:35]
	v_mfma_f32_16x16x32_bf16 v[60:63], v[148:151], v[174:177], v[60:63]
	v_mfma_f32_16x16x32_bf16 v[56:59], v[166:169], v[174:177], v[56:59]
	v_mfma_f32_16x16x32_bf16 v[52:55], v[148:151], v[182:185], v[52:55]
	v_mfma_f32_16x16x32_bf16 v[48:51], v[166:169], v[182:185], v[48:51]
	v_mfma_f32_16x16x32_bf16 v[44:47], v[148:151], v[204:207], v[44:47]
	v_mfma_f32_16x16x32_bf16 v[40:43], v[166:169], v[204:207], v[40:43]
	v_mfma_f32_16x16x32_bf16 v[36:39], v[148:151], v[214:217], v[36:39]
	v_mfma_f32_16x16x32_bf16 v[32:35], v[166:169], v[214:217], v[32:35]
	s_setprio 0
	s_barrier
	s_add_i32 s26, s56, s39
	s_mov_b32 m0, s26
	ds_read_b128 v[170:173], v213 offset:49152
	ds_read_b128 v[174:177], v213 offset:50176
	ds_read_b128 v[178:181], v213 offset:51200
	ds_read_b128 v[182:185], v213 offset:52224
	ds_read_b128 v[186:189], v213 offset:53248
	ds_read_b128 v[204:207], v213 offset:54272
	ds_read_b128 v[208:211], v213 offset:55296
	ds_read_b128 v[214:217], v213 offset:56320
	global_load_lds_dwordx4 v192, s[62:63]
	s_add_i32 m0, s26, 0x2000
	s_add_u32 s24, s24, 0x20080
	s_addc_u32 s25, s25, 0
	s_add_i32 s26, s57, s39
	global_load_lds_dwordx4 v156, s[62:63]
	s_mov_b32 m0, s26
	s_nop 0
	global_load_lds_dwordx4 v192, s[24:25]
	s_add_i32 m0, s26, 0x2000
	s_nop 0
	global_load_lds_dwordx4 v156, s[24:25]
	s_mov_b32 m0, s48
	s_nop 0
	global_load_lds_dwordx4 v160, s[64:65]
	s_mov_b32 m0, s49
	s_nop 0
	global_load_lds_dwordx4 v158, s[64:65]
	s_waitcnt vmcnt(8)
	s_waitcnt lgkmcnt(0)
	s_barrier
	s_setprio 1
	v_mfma_f32_16x16x32_bf16 v[92:95], v[128:131], v[170:173], v[92:95]
	v_mfma_f32_16x16x32_bf16 v[88:91], v[136:139], v[170:173], v[88:91]
	v_mfma_f32_16x16x32_bf16 v[84:87], v[128:131], v[178:181], v[84:87]
	v_mfma_f32_16x16x32_bf16 v[80:83], v[136:139], v[178:181], v[80:83]
	v_mfma_f32_16x16x32_bf16 v[76:79], v[128:131], v[186:189], v[76:79]
	v_mfma_f32_16x16x32_bf16 v[72:75], v[136:139], v[186:189], v[72:75]
	v_mfma_f32_16x16x32_bf16 v[68:71], v[128:131], v[208:211], v[68:71]
	v_mfma_f32_16x16x32_bf16 v[64:67], v[136:139], v[208:211], v[64:67]
	v_mfma_f32_16x16x32_bf16 v[92:95], v[132:135], v[174:177], v[92:95]
	v_mfma_f32_16x16x32_bf16 v[88:91], v[140:143], v[174:177], v[88:91]
	v_mfma_f32_16x16x32_bf16 v[84:87], v[132:135], v[182:185], v[84:87]
	v_mfma_f32_16x16x32_bf16 v[80:83], v[140:143], v[182:185], v[80:83]
	v_mfma_f32_16x16x32_bf16 v[76:79], v[132:135], v[204:207], v[76:79]
	v_mfma_f32_16x16x32_bf16 v[72:75], v[140:143], v[204:207], v[72:75]
	v_mfma_f32_16x16x32_bf16 v[68:71], v[132:135], v[214:217], v[68:71]
	v_mfma_f32_16x16x32_bf16 v[64:67], v[140:143], v[214:217], v[64:67]
	v_mfma_f32_16x16x32_bf16 v[28:31], v[144:147], v[170:173], v[28:31]
	v_mfma_f32_16x16x32_bf16 v[24:27], v[152:155], v[170:173], v[24:27]
	v_mfma_f32_16x16x32_bf16 v[20:23], v[144:147], v[178:181], v[20:23]
	v_mfma_f32_16x16x32_bf16 v[16:19], v[152:155], v[178:181], v[16:19]
	v_mfma_f32_16x16x32_bf16 v[12:15], v[144:147], v[186:189], v[12:15]
	v_mfma_f32_16x16x32_bf16 v[8:11], v[152:155], v[186:189], v[8:11]
	v_mfma_f32_16x16x32_bf16 v[4:7], v[144:147], v[208:211], v[4:7]
	v_mfma_f32_16x16x32_bf16 v[0:3], v[152:155], v[208:211], v[0:3]
	v_mfma_f32_16x16x32_bf16 v[28:31], v[148:151], v[174:177], v[28:31]
	v_mfma_f32_16x16x32_bf16 v[24:27], v[166:169], v[174:177], v[24:27]
	v_mfma_f32_16x16x32_bf16 v[20:23], v[148:151], v[182:185], v[20:23]
	v_mfma_f32_16x16x32_bf16 v[16:19], v[166:169], v[182:185], v[16:19]
	v_mfma_f32_16x16x32_bf16 v[12:15], v[148:151], v[204:207], v[12:15]
	v_mfma_f32_16x16x32_bf16 v[8:11], v[166:169], v[204:207], v[8:11]
	v_mfma_f32_16x16x32_bf16 v[4:7], v[148:151], v[214:217], v[4:7]
	v_mfma_f32_16x16x32_bf16 v[0:3], v[166:169], v[214:217], v[0:3]
	s_setprio 0
	s_barrier
	s_add_i32 s55, s55, 2
	s_add_u32 s22, s22, 0x100
	s_addc_u32 s23, s23, 0
	s_add_u32 s53, s53, 0x100
	s_addc_u32 s54, s54, 0
	s_cmp_gt_u32 s55, 5
	s_cbranch_scc0 .LBB0_1042
	s_and_b64 vcc, exec, s[10:11]
	s_cbranch_vccz .LBB0_1045
	s_barrier

; #define PG8_STAGE(bufoff, gbase, voff) do { _Pragma("unroll") for (int _i = 0; _i < 2; ++_i) \
;         __builtin_amdgcn_global_load_lds((const unsigned*)((const char*)(gbase) + (voff)[_i]), (LAS unsigned*)(lds + (bufoff) + ldsw + _i * 8192), 16, 0, 0); } while (0)
; #define PG8_LDA(dst, b, h) do { _Pragma("unroll") for (int m = 0; m < 4; ++m) _Pragma("unroll") for (int k = 0; k < 2; ++k) dst[m][k] = *(const LAS bf16x8*)(lds + PG8_SA(b, h) + aoff + m * 2048 + k * 1024); } while (0)
; #define PG8_LDB(dst, b, h) do { _Pragma("unroll") for (int n = 0; n < 2; ++n) _Pragma("unroll") for (int k = 0; k < 2; ++k) dst[n][k] = *(const LAS bf16x8*)(lds + PG8_SB(b, h) + boff + n * 2048 + k * 1024); } while (0)
; #define PG8_MMA(ai, bj, At, Bt) do { __builtin_amdgcn_s_setprio(1); _Pragma("unroll") for (int m = 0; m < 4; ++m) _Pragma("unroll") for (int n = 0; n < 2; ++n) _Pragma("unroll") for (int k = 0; k < 2; ++k) \
;         acc[ai][bj][m][n] = __builtin_amdgcn_mfma_f32_16x16x32_bf16(Bt[n][k], At[m][k], acc[ai][bj][m][n], 0, 0, 0); __builtin_amdgcn_s_setprio(0); } while (0)
; #define PG8_WAIT_V(n) asm volatile("s_waitcnt vmcnt(" #n ")" ::: "memory")
; #define PG8_WAIT_L(n) asm volatile("s_waitcnt lgkmcnt(" #n ")" ::: "memory")
; #define PG8_BAR __builtin_amdgcn_s_barrier()
; #define PG8_SCHED __builtin_amdgcn_sched_barrier(0)
; template <class EpiT, class Sched>
; __device__ __forceinline__ void gemm_phase(LAS unsigned char* lds, const Gemm g, const Sched& S, const EpiT& E, int wv) {
;     ...
;             const bool last = (t == nt - 2);
;             const char* a1 = cA + (size_t)(t + 1) * kstep;
;             const char* a2 = last ? nA : cA + (size_t)(t + 2) * kstep; const char* b2 = last ? nB : cB + (size_t)(t + 2) * kstep;
;             const char* a3 = a2 + kstep; const char* b3 = b2 + kstep;
;             PG8_LDB(B0, 0, 0); PG8_LDB(B1, 0, 1); PG8_SCHED; PG8_LDA(At, 0, 0); PG8_STAGE(PG8_SA(1, 1), a1 + hstepA, voffA);
;             PG8_WAIT_V(8); PG8_WAIT_L(0); PG8_BAR; PG8_MMA(0, 0, At, B0); PG8_MMA(0, 1, At, B1); PG8_BAR; PG8_SCHED;
;             PG8_LDA(At, 0, 1); PG8_STAGE(PG8_SB(0, 0), b2, voffB); PG8_STAGE(PG8_SB(0, 1), b2 + hstepB, voffB); PG8_STAGE(PG8_SA(0, 0), a2, voffA);
;             PG8_WAIT_V(8); PG8_WAIT_L(0); PG8_BAR; PG8_MMA(1, 0, At, B0); PG8_MMA(1, 1, At, B1); PG8_BAR; PG8_SCHED;
.LBB0_1154:
	s_add_u32 s38, s4, 0xfffc0080
	s_addc_u32 s39, s5, -1
	s_add_i32 s90, 0, 0x10000
	s_cmp_eq_u32 s89, 12
	s_cselect_b32 s41, s1, s39
	s_cselect_b32 s40, s25, s38
	s_cselect_b32 s39, s23, s65
	s_cselect_b32 s38, s33, s64
	s_add_i32 vcc_lo, 0, 0x14000
	ds_read_b128 v[120:123], v250
	ds_read_b128 v[124:127], v250 offset:1024
	ds_read_b128 v[136:139], v250 offset:2048
	ds_read_b128 v[140:143], v250 offset:3072
	ds_read_b128 v[144:147], v251
	ds_read_b128 v[148:151], v251 offset:1024
	ds_read_b128 v[152:155], v251 offset:2048
	ds_read_b128 v[156:159], v251 offset:3072
	s_add_i32 m0, s27, 0xc000
	ds_read_b128 v[160:163], v241
	ds_read_b128 v[164:167], v241 offset:1024
	ds_read_b128 v[178:181], v241 offset:2048
	ds_read_b128 v[182:185], v241 offset:3072
	ds_read_b128 v[186:189], v241 offset:4096
	ds_read_b128 v[204:207], v241 offset:5120
	ds_read_b128 v[208:211], v241 offset:6144
	ds_read_b128 v[212:215], v241 offset:7168
	global_load_lds_dwordx4 v174, s[4:5]
	s_add_i32 m0, s27, 0xe000
	s_nop 0
	global_load_lds_dwordx4 v176, s[4:5]
	s_waitcnt vmcnt(8)
	s_waitcnt lgkmcnt(0)
	s_barrier
	s_setprio 1
	v_mfma_f32_16x16x32_bf16 v[132:135], v[120:123], v[160:163], v[132:135]
	v_mfma_f32_16x16x32_bf16 v[128:131], v[136:139], v[160:163], v[128:131]
	v_mfma_f32_16x16x32_bf16 v[116:119], v[120:123], v[178:181], v[116:119]
	v_mfma_f32_16x16x32_bf16 v[112:115], v[136:139], v[178:181], v[112:115]
	v_mfma_f32_16x16x32_bf16 v[108:111], v[120:123], v[186:189], v[108:111]
	v_mfma_f32_16x16x32_bf16 v[104:107], v[136:139], v[186:189], v[104:107]
	v_mfma_f32_16x16x32_bf16 v[100:103], v[120:123], v[208:211], v[100:103]
	v_mfma_f32_16x16x32_bf16 v[96:99], v[136:139], v[208:211], v[96:99]
	v_mfma_f32_16x16x32_bf16 v[132:135], v[124:127], v[164:167], v[132:135]
	v_mfma_f32_16x16x32_bf16 v[128:131], v[140:143], v[164:167], v[128:131]
	v_mfma_f32_16x16x32_bf16 v[116:119], v[124:127], v[182:185], v[116:119]
	v_mfma_f32_16x16x32_bf16 v[112:115], v[140:143], v[182:185], v[112:115]
	v_mfma_f32_16x16x32_bf16 v[108:111], v[124:127], v[204:207], v[108:111]
	v_mfma_f32_16x16x32_bf16 v[104:107], v[140:143], v[204:207], v[104:107]
	v_mfma_f32_16x16x32_bf16 v[100:103], v[124:127], v[212:215], v[100:103]
	v_mfma_f32_16x16x32_bf16 v[96:99], v[140:143], v[212:215], v[96:99]
	v_mfma_f32_16x16x32_bf16 v[60:63], v[144:147], v[160:163], v[60:63]
	v_mfma_f32_16x16x32_bf16 v[56:59], v[152:155], v[160:163], v[56:59]
	v_mfma_f32_16x16x32_bf16 v[52:55], v[144:147], v[178:181], v[52:55]
	v_mfma_f32_16x16x32_bf16 v[48:51], v[152:155], v[178:181], v[48:51]
	v_mfma_f32_16x16x32_bf16 v[44:47], v[144:147], v[186:189], v[44:47]
	v_mfma_f32_16x16x32_bf16 v[40:43], v[152:155], v[186:189], v[40:43]
	v_mfma_f32_16x16x32_bf16 v[36:39], v[144:147], v[208:211], v[36:39]
	v_mfma_f32_16x16x32_bf16 v[32:35], v[152:155], v[208:211], v[32:35]
	v_mfma_f32_16x16x32_bf16 v[60:63], v[148:151], v[164:167], v[60:63]
	v_mfma_f32_16x16x32_bf16 v[56:59], v[156:159], v[164:167], v[56:59]
	v_mfma_f32_16x16x32_bf16 v[52:55], v[148:151], v[182:185], v[52:55]
	v_mfma_f32_16x16x32_bf16 v[48:51], v[156:159], v[182:185], v[48:51]
	v_mfma_f32_16x16x32_bf16 v[44:47], v[148:151], v[204:207], v[44:47]
	v_mfma_f32_16x16x32_bf16 v[40:43], v[156:159], v[204:207], v[40:43]
	v_mfma_f32_16x16x32_bf16 v[36:39], v[148:151], v[212:215], v[36:39]
	v_mfma_f32_16x16x32_bf16 v[32:35], v[156:159], v[212:215], v[32:35]
	s_setprio 0
	s_barrier
	s_add_i32 s90, s90, s48
	s_add_u32 s36, s38, s92
	s_addc_u32 s37, s39, s93
	s_mov_b32 m0, s90
	ds_read_b128 v[160:163], v241 offset:16384
	ds_read_b128 v[164:167], v241 offset:17408
	ds_read_b128 v[178:181], v241 offset:18432
	ds_read_b128 v[182:185], v241 offset:19456
	ds_read_b128 v[186:189], v241 offset:20480
	ds_read_b128 v[204:207], v241 offset:21504
	ds_read_b128 v[208:211], v241 offset:22528
	ds_read_b128 v[212:215], v241 offset:23552
	global_load_lds_dwordx4 v192, s[38:39]
	s_add_i32 m0, s90, 0x2000
	s_add_u32 s90, s38, 0x100000
	s_addc_u32 s91, s39, 0
	s_add_i32 vcc_lo, vcc_lo, s48
	global_load_lds_dwordx4 v172, s[38:39]
	s_mov_b32 m0, vcc_lo
	s_nop 0
	global_load_lds_dwordx4 v192, s[90:91]
	s_add_i32 m0, vcc_lo, 0x2000
	s_nop 0
	global_load_lds_dwordx4 v172, s[90:91]
	s_add_u32 s98, s40, s92
	s_addc_u32 s99, s41, s93
	s_mov_b32 m0, s27
	s_nop 0
	global_load_lds_dwordx4 v168, s[40:41]
	s_mov_b32 m0, s53
	s_nop 0
	global_load_lds_dwordx4 v170, s[40:41]
	s_waitcnt vmcnt(8)
	s_waitcnt lgkmcnt(0)
	s_barrier
	s_setprio 1
	v_mfma_f32_16x16x32_bf16 v[92:95], v[120:123], v[160:163], v[92:95]
	v_mfma_f32_16x16x32_bf16 v[88:91], v[136:139], v[160:163], v[88:91]
	v_mfma_f32_16x16x32_bf16 v[84:87], v[120:123], v[178:181], v[84:87]
	v_mfma_f32_16x16x32_bf16 v[80:83], v[136:139], v[178:181], v[80:83]
	v_mfma_f32_16x16x32_bf16 v[76:79], v[120:123], v[186:189], v[76:79]
	v_mfma_f32_16x16x32_bf16 v[72:75], v[136:139], v[186:189], v[72:75]
	v_mfma_f32_16x16x32_bf16 v[68:71], v[120:123], v[208:211], v[68:71]
	v_mfma_f32_16x16x32_bf16 v[64:67], v[136:139], v[208:211], v[64:67]
	v_mfma_f32_16x16x32_bf16 v[92:95], v[124:127], v[164:167], v[92:95]
	v_mfma_f32_16x16x32_bf16 v[88:91], v[140:143], v[164:167], v[88:91]
	v_mfma_f32_16x16x32_bf16 v[84:87], v[124:127], v[182:185], v[84:87]
	v_mfma_f32_16x16x32_bf16 v[80:83], v[140:143], v[182:185], v[80:83]
	v_mfma_f32_16x16x32_bf16 v[76:79], v[124:127], v[204:207], v[76:79]
	v_mfma_f32_16x16x32_bf16 v[72:75], v[140:143], v[204:207], v[72:75]
	v_mfma_f32_16x16x32_bf16 v[68:71], v[124:127], v[212:215], v[68:71]
	v_mfma_f32_16x16x32_bf16 v[64:67], v[140:143], v[212:215], v[64:67]
	v_mfma_f32_16x16x32_bf16 v[28:31], v[144:147], v[160:163], v[28:31]
	v_mfma_f32_16x16x32_bf16 v[24:27], v[152:155], v[160:163], v[24:27]
	v_mfma_f32_16x16x32_bf16 v[20:23], v[144:147], v[178:181], v[20:23]
	v_mfma_f32_16x16x32_bf16 v[16:19], v[152:155], v[178:181], v[16:19]
	v_mfma_f32_16x16x32_bf16 v[12:15], v[144:147], v[186:189], v[12:15]
	v_mfma_f32_16x16x32_bf16 v[8:11], v[152:155], v[186:189], v[8:11]
	v_mfma_f32_16x16x32_bf16 v[4:7], v[144:147], v[208:211], v[4:7]
	v_mfma_f32_16x16x32_bf16 v[0:3], v[152:155], v[208:211], v[0:3]
	v_mfma_f32_16x16x32_bf16 v[28:31], v[148:151], v[164:167], v[28:31]
	v_mfma_f32_16x16x32_bf16 v[24:27], v[156:159], v[164:167], v[24:27]
	v_mfma_f32_16x16x32_bf16 v[20:23], v[148:151], v[182:185], v[20:23]
	v_mfma_f32_16x16x32_bf16 v[16:19], v[156:159], v[182:185], v[16:19]
	v_mfma_f32_16x16x32_bf16 v[12:15], v[148:151], v[204:207], v[12:15]
	v_mfma_f32_16x16x32_bf16 v[8:11], v[156:159], v[204:207], v[8:11]
	v_mfma_f32_16x16x32_bf16 v[4:7], v[148:151], v[212:215], v[4:7]
	v_mfma_f32_16x16x32_bf16 v[0:3], v[156:159], v[212:215], v[0:3]
	s_setprio 0
	s_barrier
; #define PG8_STAGE(bufoff, gbase, voff) do { _Pragma("unroll") for (int _i = 0; _i < 2; ++_i) \
;         __builtin_amdgcn_global_load_lds((const unsigned*)((const char*)(gbase) + (voff)[_i]), (LAS unsigned*)(lds + (bufoff) + ldsw + _i * 8192), 16, 0, 0); } while (0)
; #define PG8_LDA(dst, b, h) do { _Pragma("unroll") for (int m = 0; m < 4; ++m) _Pragma("unroll") for (int k = 0; k < 2; ++k) dst[m][k] = *(const LAS bf16x8*)(lds + PG8_SA(b, h) + aoff + m * 2048 + k * 1024); } while (0)
; #define PG8_LDB(dst, b, h) do { _Pragma("unroll") for (int n = 0; n < 2; ++n) _Pragma("unroll") for (int k = 0; k < 2; ++k) dst[n][k] = *(const LAS bf16x8*)(lds + PG8_SB(b, h) + boff + n * 2048 + k * 1024); } while (0)
; #define PG8_MMA(ai, bj, At, Bt) do { __builtin_amdgcn_s_setprio(1); _Pragma("unroll") for (int m = 0; m < 4; ++m) _Pragma("unroll") for (int n = 0; n < 2; ++n) _Pragma("unroll") for (int k = 0; k < 2; ++k) \
;         acc[ai][bj][m][n] = __builtin_amdgcn_mfma_f32_16x16x32_bf16(Bt[n][k], At[m][k], acc[ai][bj][m][n], 0, 0, 0); __builtin_amdgcn_s_setprio(0); } while (0)
; #define PG8_WAIT_V(n) asm volatile("s_waitcnt vmcnt(" #n ")" ::: "memory")
; #define PG8_WAIT_L(n) asm volatile("s_waitcnt lgkmcnt(" #n ")" ::: "memory")
; #define PG8_BAR __builtin_amdgcn_s_barrier()
; #define PG8_SCHED __builtin_amdgcn_sched_barrier(0)
; template <class EpiT, class Sched>
; __device__ __forceinline__ void gemm_phase(LAS unsigned char* lds, const Gemm g, const Sched& S, const EpiT& E, int wv) {
;     ...
;             PG8_LDB(B0, 1, 0); PG8_LDB(B1, 1, 1); PG8_SCHED; PG8_LDA(At, 1, 0); PG8_STAGE(PG8_SA(0, 1), a2 + hstepA, voffA);
;             PG8_WAIT_V(8); PG8_WAIT_L(0); PG8_BAR; PG8_MMA(0, 0, At, B0); PG8_MMA(0, 1, At, B1); PG8_BAR; PG8_SCHED;
;             PG8_LDA(At, 1, 1); PG8_STAGE(PG8_SB(1, 0), b3, voffB); PG8_STAGE(PG8_SB(1, 1), b3 + hstepB, voffB); PG8_STAGE(PG8_SA(1, 0), a3, voffA);
;             PG8_WAIT_V(8); PG8_WAIT_L(0); PG8_BAR; PG8_MMA(1, 0, At, B0); PG8_MMA(1, 1, At, B1); PG8_BAR; PG8_SCHED;
;         }
;         if (wr == 0) PG8_BAR;
	s_add_i32 s90, 0, 0x18000
	s_add_i32 s91, 0, 0x1c000
	ds_read_b128 v[120:123], v252
	ds_read_b128 v[124:127], v252 offset:1024
	ds_read_b128 v[136:139], v252 offset:2048
	ds_read_b128 v[140:143], v252 offset:3072
	ds_read_b128 v[144:147], v253
	ds_read_b128 v[148:151], v253 offset:1024
	ds_read_b128 v[152:155], v253 offset:2048
	ds_read_b128 v[156:159], v253 offset:3072
	s_add_u32 s40, s40, 0x40000
	s_addc_u32 s41, s41, 0
	s_mov_b32 m0, s54
	ds_read_b128 v[160:163], v241 offset:32768
	ds_read_b128 v[164:167], v241 offset:33792
	ds_read_b128 v[178:181], v241 offset:34816
	ds_read_b128 v[182:185], v241 offset:35840
	ds_read_b128 v[186:189], v241 offset:36864
	ds_read_b128 v[204:207], v241 offset:37888
	ds_read_b128 v[208:211], v241 offset:38912
	ds_read_b128 v[212:215], v241 offset:39936
	global_load_lds_dwordx4 v168, s[40:41]
	s_mov_b32 m0, s55
	s_nop 0
	global_load_lds_dwordx4 v170, s[40:41]
	s_waitcnt vmcnt(8)
	s_waitcnt lgkmcnt(0)
	s_barrier
	s_setprio 1
	v_mfma_f32_16x16x32_bf16 v[132:135], v[120:123], v[160:163], v[132:135]
	v_mfma_f32_16x16x32_bf16 v[128:131], v[136:139], v[160:163], v[128:131]
	v_mfma_f32_16x16x32_bf16 v[116:119], v[120:123], v[178:181], v[116:119]
	v_mfma_f32_16x16x32_bf16 v[112:115], v[136:139], v[178:181], v[112:115]
	v_mfma_f32_16x16x32_bf16 v[108:111], v[120:123], v[186:189], v[108:111]
	v_mfma_f32_16x16x32_bf16 v[104:107], v[136:139], v[186:189], v[104:107]
	v_mfma_f32_16x16x32_bf16 v[100:103], v[120:123], v[208:211], v[100:103]
	v_mfma_f32_16x16x32_bf16 v[96:99], v[136:139], v[208:211], v[96:99]
	v_mfma_f32_16x16x32_bf16 v[132:135], v[124:127], v[164:167], v[132:135]
	v_mfma_f32_16x16x32_bf16 v[128:131], v[140:143], v[164:167], v[128:131]
	v_mfma_f32_16x16x32_bf16 v[116:119], v[124:127], v[182:185], v[116:119]
	v_mfma_f32_16x16x32_bf16 v[112:115], v[140:143], v[182:185], v[112:115]
	v_mfma_f32_16x16x32_bf16 v[108:111], v[124:127], v[204:207], v[108:111]
	v_mfma_f32_16x16x32_bf16 v[104:107], v[140:143], v[204:207], v[104:107]
	v_mfma_f32_16x16x32_bf16 v[100:103], v[124:127], v[212:215], v[100:103]
	v_mfma_f32_16x16x32_bf16 v[96:99], v[140:143], v[212:215], v[96:99]
	v_mfma_f32_16x16x32_bf16 v[60:63], v[144:147], v[160:163], v[60:63]
	v_mfma_f32_16x16x32_bf16 v[56:59], v[152:155], v[160:163], v[56:59]
	v_mfma_f32_16x16x32_bf16 v[52:55], v[144:147], v[178:181], v[52:55]
	v_mfma_f32_16x16x32_bf16 v[48:51], v[152:155], v[178:181], v[48:51]
	v_mfma_f32_16x16x32_bf16 v[44:47], v[144:147], v[186:189], v[44:47]
	v_mfma_f32_16x16x32_bf16 v[40:43], v[152:155], v[186:189], v[40:43]
	v_mfma_f32_16x16x32_bf16 v[36:39], v[144:147], v[208:211], v[36:39]
	v_mfma_f32_16x16x32_bf16 v[32:35], v[152:155], v[208:211], v[32:35]
	v_mfma_f32_16x16x32_bf16 v[60:63], v[148:151], v[164:167], v[60:63]
	v_mfma_f32_16x16x32_bf16 v[56:59], v[156:159], v[164:167], v[56:59]
	v_mfma_f32_16x16x32_bf16 v[52:55], v[148:151], v[182:185], v[52:55]
	v_mfma_f32_16x16x32_bf16 v[48:51], v[156:159], v[182:185], v[48:51]
	v_mfma_f32_16x16x32_bf16 v[44:47], v[148:151], v[204:207], v[44:47]
	v_mfma_f32_16x16x32_bf16 v[40:43], v[156:159], v[204:207], v[40:43]
	v_mfma_f32_16x16x32_bf16 v[36:39], v[148:151], v[212:215], v[36:39]
	v_mfma_f32_16x16x32_bf16 v[32:35], v[156:159], v[212:215], v[32:35]
	s_setprio 0
	s_barrier
	s_add_i32 s40, s90, s48
	s_mov_b32 m0, s40
	ds_read_b128 v[160:163], v241 offset:49152
	ds_read_b128 v[164:167], v241 offset:50176
	ds_read_b128 v[178:181], v241 offset:51200
	ds_read_b128 v[182:185], v241 offset:52224
	ds_read_b128 v[186:189], v241 offset:53248
	ds_read_b128 v[204:207], v241 offset:54272
	ds_read_b128 v[208:211], v241 offset:55296
	ds_read_b128 v[212:215], v241 offset:56320
	global_load_lds_dwordx4 v192, s[36:37]
	s_add_i32 m0, s40, 0x2000
	s_add_u32 s38, s38, 0x100080
	s_addc_u32 s39, s39, 0
	s_add_i32 s40, s91, s48
	global_load_lds_dwordx4 v172, s[36:37]
	s_mov_b32 m0, s40
	s_nop 0
	global_load_lds_dwordx4 v192, s[38:39]
	s_add_i32 m0, s40, 0x2000
	s_nop 0
	global_load_lds_dwordx4 v172, s[38:39]
	s_mov_b32 m0, s62
	s_nop 0
	global_load_lds_dwordx4 v168, s[98:99]
	s_mov_b32 m0, s63
	s_nop 0
	global_load_lds_dwordx4 v170, s[98:99]
	s_waitcnt vmcnt(8)
	s_waitcnt lgkmcnt(0)
	s_barrier
	s_setprio 1
	v_mfma_f32_16x16x32_bf16 v[92:95], v[120:123], v[160:163], v[92:95]
	v_mfma_f32_16x16x32_bf16 v[88:91], v[136:139], v[160:163], v[88:91]
	v_mfma_f32_16x16x32_bf16 v[84:87], v[120:123], v[178:181], v[84:87]
	v_mfma_f32_16x16x32_bf16 v[80:83], v[136:139], v[178:181], v[80:83]
	v_mfma_f32_16x16x32_bf16 v[76:79], v[120:123], v[186:189], v[76:79]
	v_mfma_f32_16x16x32_bf16 v[72:75], v[136:139], v[186:189], v[72:75]
	v_mfma_f32_16x16x32_bf16 v[68:71], v[120:123], v[208:211], v[68:71]
	v_mfma_f32_16x16x32_bf16 v[64:67], v[136:139], v[208:211], v[64:67]
	v_mfma_f32_16x16x32_bf16 v[92:95], v[124:127], v[164:167], v[92:95]
	v_mfma_f32_16x16x32_bf16 v[88:91], v[140:143], v[164:167], v[88:91]
	v_mfma_f32_16x16x32_bf16 v[84:87], v[124:127], v[182:185], v[84:87]
	v_mfma_f32_16x16x32_bf16 v[80:83], v[140:143], v[182:185], v[80:83]
	v_mfma_f32_16x16x32_bf16 v[76:79], v[124:127], v[204:207], v[76:79]
	v_mfma_f32_16x16x32_bf16 v[72:75], v[140:143], v[204:207], v[72:75]
	v_mfma_f32_16x16x32_bf16 v[68:71], v[124:127], v[212:215], v[68:71]
	v_mfma_f32_16x16x32_bf16 v[64:67], v[140:143], v[212:215], v[64:67]
	v_mfma_f32_16x16x32_bf16 v[28:31], v[144:147], v[160:163], v[28:31]
	v_mfma_f32_16x16x32_bf16 v[24:27], v[152:155], v[160:163], v[24:27]
	v_mfma_f32_16x16x32_bf16 v[20:23], v[144:147], v[178:181], v[20:23]
	v_mfma_f32_16x16x32_bf16 v[16:19], v[152:155], v[178:181], v[16:19]
	v_mfma_f32_16x16x32_bf16 v[12:15], v[144:147], v[186:189], v[12:15]
	v_mfma_f32_16x16x32_bf16 v[8:11], v[152:155], v[186:189], v[8:11]
	v_mfma_f32_16x16x32_bf16 v[4:7], v[144:147], v[208:211], v[4:7]
	v_mfma_f32_16x16x32_bf16 v[0:3], v[152:155], v[208:211], v[0:3]
	v_mfma_f32_16x16x32_bf16 v[28:31], v[148:151], v[164:167], v[28:31]
	v_mfma_f32_16x16x32_bf16 v[24:27], v[156:159], v[164:167], v[24:27]
	v_mfma_f32_16x16x32_bf16 v[20:23], v[148:151], v[182:185], v[20:23]
	v_mfma_f32_16x16x32_bf16 v[16:19], v[156:159], v[182:185], v[16:19]
	v_mfma_f32_16x16x32_bf16 v[12:15], v[148:151], v[204:207], v[12:15]
	v_mfma_f32_16x16x32_bf16 v[8:11], v[156:159], v[204:207], v[8:11]
	v_mfma_f32_16x16x32_bf16 v[4:7], v[148:151], v[212:215], v[4:7]
	v_mfma_f32_16x16x32_bf16 v[0:3], v[156:159], v[212:215], v[0:3]
	s_setprio 0
	s_barrier
	s_add_i32 s89, s89, 2
	s_add_u32 s4, s4, 0x100
	s_addc_u32 s5, s5, 0
	s_add_u32 s64, s64, 0x100
	s_addc_u32 s65, s65, 0
	s_cmp_gt_u32 s89, 13
	s_cbranch_scc0 .LBB0_1154
	s_and_b64 vcc, exec, s[20:21]
	s_cbranch_vccz .LBB0_1157
	s_barrier

; #define PG8_STAGE(bufoff, gbase, voff) do { _Pragma("unroll") for (int _i = 0; _i < 2; ++_i) \
;         __builtin_amdgcn_global_load_lds((const unsigned*)((const char*)(gbase) + (voff)[_i]), (LAS unsigned*)(lds + (bufoff) + ldsw + _i * 8192), 16, 0, 0); } while (0)
; #define PG8_LDA(dst, b, h) do { _Pragma("unroll") for (int m = 0; m < 4; ++m) _Pragma("unroll") for (int k = 0; k < 2; ++k) dst[m][k] = *(const LAS bf16x8*)(lds + PG8_SA(b, h) + aoff + m * 2048 + k * 1024); } while (0)
; #define PG8_LDB(dst, b, h) do { _Pragma("unroll") for (int n = 0; n < 2; ++n) _Pragma("unroll") for (int k = 0; k < 2; ++k) dst[n][k] = *(const LAS bf16x8*)(lds + PG8_SB(b, h) + boff + n * 2048 + k * 1024); } while (0)
; #define PG8_MMA(ai, bj, At, Bt) do { __builtin_amdgcn_s_setprio(1); _Pragma("unroll") for (int m = 0; m < 4; ++m) _Pragma("unroll") for (int n = 0; n < 2; ++n) _Pragma("unroll") for (int k = 0; k < 2; ++k) \
;         acc[ai][bj][m][n] = __builtin_amdgcn_mfma_f32_16x16x32_bf16(Bt[n][k], At[m][k], acc[ai][bj][m][n], 0, 0, 0); __builtin_amdgcn_s_setprio(0); } while (0)
; #define PG8_WAIT_V(n) asm volatile("s_waitcnt vmcnt(" #n ")" ::: "memory")
; #define PG8_WAIT_L(n) asm volatile("s_waitcnt lgkmcnt(" #n ")" ::: "memory")
; #define PG8_BAR __builtin_amdgcn_s_barrier()
; #define PG8_SCHED __builtin_amdgcn_sched_barrier(0)
; template <class EpiT, class Sched>
; __device__ __forceinline__ void gemm_phase(LAS unsigned char* lds, const Gemm g, const Sched& S, const EpiT& E, int wv) {
;     ...
;             const bool last = (t == nt - 2);
;             const char* a1 = cA + (size_t)(t + 1) * kstep;
;             const char* a2 = last ? nA : cA + (size_t)(t + 2) * kstep; const char* b2 = last ? nB : cB + (size_t)(t + 2) * kstep;
;             const char* a3 = a2 + kstep; const char* b3 = b2 + kstep;
;             PG8_LDB(B0, 0, 0); PG8_LDB(B1, 0, 1); PG8_SCHED; PG8_LDA(At, 0, 0); PG8_STAGE(PG8_SA(1, 1), a1 + hstepA, voffA);
;             PG8_WAIT_V(8); PG8_WAIT_L(0); PG8_BAR; PG8_MMA(0, 0, At, B0); PG8_MMA(0, 1, At, B1); PG8_BAR; PG8_SCHED;
;             PG8_LDA(At, 0, 1); PG8_STAGE(PG8_SB(0, 0), b2, voffB); PG8_STAGE(PG8_SB(0, 1), b2 + hstepB, voffB); PG8_STAGE(PG8_SA(0, 0), a2, voffA);
;             PG8_WAIT_V(8); PG8_WAIT_L(0); PG8_BAR; PG8_MMA(1, 0, At, B0); PG8_MMA(1, 1, At, B1); PG8_BAR; PG8_SCHED;
.LBB0_1271:
	s_add_u32 s24, s22, 0xfffc0080
	s_addc_u32 s25, s23, -1
	s_add_i32 s56, 0, 0x10000
	s_cmp_eq_u32 s55, 12
	s_cselect_b32 s27, s13, s25
	s_cselect_b32 s26, s51, s24
	s_cselect_b32 s25, s11, s54
	s_cselect_b32 s24, s52, s53
	s_add_i32 s58, 0, 0x14000
	ds_read_b128 v[128:131], v250
	ds_read_b128 v[132:135], v250 offset:1024
	ds_read_b128 v[146:149], v250 offset:2048
	ds_read_b128 v[150:153], v250 offset:3072
	ds_read_b128 v[154:157], v251
	ds_read_b128 v[160:163], v251 offset:1024
	ds_read_b128 v[164:167], v251 offset:2048
	ds_read_b128 v[168:171], v251 offset:3072
	s_add_i32 m0, s19, 0xc000
	ds_read_b128 v[172:175], v159
	ds_read_b128 v[176:179], v159 offset:1024
	ds_read_b128 v[180:183], v159 offset:2048
	ds_read_b128 v[184:187], v159 offset:3072
	ds_read_b128 v[188:191], v159 offset:4096
	ds_read_b128 v[204:207], v159 offset:5120
	ds_read_b128 v[208:211], v159 offset:6144
	ds_read_b128 v[212:215], v159 offset:7168
	global_load_lds_dwordx4 v142, s[22:23]
	s_add_i32 m0, s19, 0xe000
	s_nop 0
	global_load_lds_dwordx4 v144, s[22:23]
	s_waitcnt vmcnt(8)
	s_waitcnt lgkmcnt(0)
	s_barrier
	s_setprio 1
	v_mfma_f32_16x16x32_bf16 v[124:127], v[128:131], v[172:175], v[124:127]
	v_mfma_f32_16x16x32_bf16 v[120:123], v[146:149], v[172:175], v[120:123]
	v_mfma_f32_16x16x32_bf16 v[116:119], v[128:131], v[180:183], v[116:119]
	v_mfma_f32_16x16x32_bf16 v[112:115], v[146:149], v[180:183], v[112:115]
	v_mfma_f32_16x16x32_bf16 v[108:111], v[128:131], v[188:191], v[108:111]
	v_mfma_f32_16x16x32_bf16 v[104:107], v[146:149], v[188:191], v[104:107]
	v_mfma_f32_16x16x32_bf16 v[100:103], v[128:131], v[208:211], v[100:103]
	v_mfma_f32_16x16x32_bf16 v[96:99], v[146:149], v[208:211], v[96:99]
	v_mfma_f32_16x16x32_bf16 v[124:127], v[132:135], v[176:179], v[124:127]
	v_mfma_f32_16x16x32_bf16 v[120:123], v[150:153], v[176:179], v[120:123]
	v_mfma_f32_16x16x32_bf16 v[116:119], v[132:135], v[184:187], v[116:119]
	v_mfma_f32_16x16x32_bf16 v[112:115], v[150:153], v[184:187], v[112:115]
	v_mfma_f32_16x16x32_bf16 v[108:111], v[132:135], v[204:207], v[108:111]
	v_mfma_f32_16x16x32_bf16 v[104:107], v[150:153], v[204:207], v[104:107]
	v_mfma_f32_16x16x32_bf16 v[100:103], v[132:135], v[212:215], v[100:103]
	v_mfma_f32_16x16x32_bf16 v[96:99], v[150:153], v[212:215], v[96:99]
	v_mfma_f32_16x16x32_bf16 v[68:71], v[154:157], v[172:175], v[68:71]
	v_mfma_f32_16x16x32_bf16 v[64:67], v[164:167], v[172:175], v[64:67]
	v_mfma_f32_16x16x32_bf16 v[52:55], v[154:157], v[180:183], v[52:55]
	v_mfma_f32_16x16x32_bf16 v[48:51], v[164:167], v[180:183], v[48:51]
	v_mfma_f32_16x16x32_bf16 v[44:47], v[154:157], v[188:191], v[44:47]
	v_mfma_f32_16x16x32_bf16 v[40:43], v[164:167], v[188:191], v[40:43]
	v_mfma_f32_16x16x32_bf16 v[36:39], v[154:157], v[208:211], v[36:39]
	v_mfma_f32_16x16x32_bf16 v[32:35], v[164:167], v[208:211], v[32:35]
	v_mfma_f32_16x16x32_bf16 v[68:71], v[160:163], v[176:179], v[68:71]
	v_mfma_f32_16x16x32_bf16 v[64:67], v[168:171], v[176:179], v[64:67]
	v_mfma_f32_16x16x32_bf16 v[52:55], v[160:163], v[184:187], v[52:55]
	v_mfma_f32_16x16x32_bf16 v[48:51], v[168:171], v[184:187], v[48:51]
	v_mfma_f32_16x16x32_bf16 v[44:47], v[160:163], v[204:207], v[44:47]
	v_mfma_f32_16x16x32_bf16 v[40:43], v[168:171], v[204:207], v[40:43]
	v_mfma_f32_16x16x32_bf16 v[36:39], v[160:163], v[212:215], v[36:39]
	v_mfma_f32_16x16x32_bf16 v[32:35], v[168:171], v[212:215], v[32:35]
	s_setprio 0
	s_barrier
	s_add_i32 s56, s56, s33
	s_add_u32 s62, s24, s92
	s_addc_u32 s63, s25, s93
	s_mov_b32 m0, s56
	ds_read_b128 v[172:175], v159 offset:16384
	ds_read_b128 v[176:179], v159 offset:17408
	ds_read_b128 v[180:183], v159 offset:18432
	ds_read_b128 v[184:187], v159 offset:19456
	ds_read_b128 v[188:191], v159 offset:20480
	ds_read_b128 v[204:207], v159 offset:21504
	ds_read_b128 v[208:211], v159 offset:22528
	ds_read_b128 v[212:215], v159 offset:23552
	global_load_lds_dwordx4 v192, s[24:25]
	s_add_i32 m0, s56, 0x2000
	s_add_u32 s56, s24, 0x40000
	s_addc_u32 s57, s25, 0
	s_add_i32 s58, s58, s33
	global_load_lds_dwordx4 v140, s[24:25]
	s_mov_b32 m0, s58
	s_nop 0
	global_load_lds_dwordx4 v192, s[56:57]
	s_add_i32 m0, s58, 0x2000
	s_nop 0
	global_load_lds_dwordx4 v140, s[56:57]
	s_add_u32 s64, s26, s92
	s_addc_u32 s65, s27, s93
	s_mov_b32 m0, s19
	s_nop 0
	global_load_lds_dwordx4 v136, s[26:27]
	s_mov_b32 m0, s21
	s_nop 0
	global_load_lds_dwordx4 v138, s[26:27]
	s_waitcnt vmcnt(8)
	s_waitcnt lgkmcnt(0)
	s_barrier
	s_setprio 1
	v_mfma_f32_16x16x32_bf16 v[92:95], v[128:131], v[172:175], v[92:95]
	v_mfma_f32_16x16x32_bf16 v[88:91], v[146:149], v[172:175], v[88:91]
	v_mfma_f32_16x16x32_bf16 v[84:87], v[128:131], v[180:183], v[84:87]
	v_mfma_f32_16x16x32_bf16 v[80:83], v[146:149], v[180:183], v[80:83]
	v_mfma_f32_16x16x32_bf16 v[76:79], v[128:131], v[188:191], v[76:79]
	v_mfma_f32_16x16x32_bf16 v[72:75], v[146:149], v[188:191], v[72:75]
	v_mfma_f32_16x16x32_bf16 v[60:63], v[128:131], v[208:211], v[60:63]
	v_mfma_f32_16x16x32_bf16 v[56:59], v[146:149], v[208:211], v[56:59]
	v_mfma_f32_16x16x32_bf16 v[92:95], v[132:135], v[176:179], v[92:95]
	v_mfma_f32_16x16x32_bf16 v[88:91], v[150:153], v[176:179], v[88:91]
	v_mfma_f32_16x16x32_bf16 v[84:87], v[132:135], v[184:187], v[84:87]
	v_mfma_f32_16x16x32_bf16 v[80:83], v[150:153], v[184:187], v[80:83]
	v_mfma_f32_16x16x32_bf16 v[76:79], v[132:135], v[204:207], v[76:79]
	v_mfma_f32_16x16x32_bf16 v[72:75], v[150:153], v[204:207], v[72:75]
	v_mfma_f32_16x16x32_bf16 v[60:63], v[132:135], v[212:215], v[60:63]
	v_mfma_f32_16x16x32_bf16 v[56:59], v[150:153], v[212:215], v[56:59]
	v_mfma_f32_16x16x32_bf16 v[28:31], v[154:157], v[172:175], v[28:31]
	v_mfma_f32_16x16x32_bf16 v[24:27], v[164:167], v[172:175], v[24:27]
	v_mfma_f32_16x16x32_bf16 v[20:23], v[154:157], v[180:183], v[20:23]
	v_mfma_f32_16x16x32_bf16 v[16:19], v[164:167], v[180:183], v[16:19]
	v_mfma_f32_16x16x32_bf16 v[12:15], v[154:157], v[188:191], v[12:15]
	v_mfma_f32_16x16x32_bf16 v[8:11], v[164:167], v[188:191], v[8:11]
	v_mfma_f32_16x16x32_bf16 v[4:7], v[154:157], v[208:211], v[4:7]
	v_mfma_f32_16x16x32_bf16 v[0:3], v[164:167], v[208:211], v[0:3]
	v_mfma_f32_16x16x32_bf16 v[28:31], v[160:163], v[176:179], v[28:31]
	v_mfma_f32_16x16x32_bf16 v[24:27], v[168:171], v[176:179], v[24:27]
	v_mfma_f32_16x16x32_bf16 v[20:23], v[160:163], v[184:187], v[20:23]
	v_mfma_f32_16x16x32_bf16 v[16:19], v[168:171], v[184:187], v[16:19]
	v_mfma_f32_16x16x32_bf16 v[12:15], v[160:163], v[204:207], v[12:15]
	v_mfma_f32_16x16x32_bf16 v[8:11], v[168:171], v[204:207], v[8:11]
	v_mfma_f32_16x16x32_bf16 v[4:7], v[160:163], v[212:215], v[4:7]
	v_mfma_f32_16x16x32_bf16 v[0:3], v[168:171], v[212:215], v[0:3]
	s_setprio 0
	s_barrier
; #define PG8_STAGE(bufoff, gbase, voff) do { _Pragma("unroll") for (int _i = 0; _i < 2; ++_i) \
;         __builtin_amdgcn_global_load_lds((const unsigned*)((const char*)(gbase) + (voff)[_i]), (LAS unsigned*)(lds + (bufoff) + ldsw + _i * 8192), 16, 0, 0); } while (0)
; #define PG8_LDA(dst, b, h) do { _Pragma("unroll") for (int m = 0; m < 4; ++m) _Pragma("unroll") for (int k = 0; k < 2; ++k) dst[m][k] = *(const LAS bf16x8*)(lds + PG8_SA(b, h) + aoff + m * 2048 + k * 1024); } while (0)
; #define PG8_LDB(dst, b, h) do { _Pragma("unroll") for (int n = 0; n < 2; ++n) _Pragma("unroll") for (int k = 0; k < 2; ++k) dst[n][k] = *(const LAS bf16x8*)(lds + PG8_SB(b, h) + boff + n * 2048 + k * 1024); } while (0)
; #define PG8_MMA(ai, bj, At, Bt) do { __builtin_amdgcn_s_setprio(1); _Pragma("unroll") for (int m = 0; m < 4; ++m) _Pragma("unroll") for (int n = 0; n < 2; ++n) _Pragma("unroll") for (int k = 0; k < 2; ++k) \
;         acc[ai][bj][m][n] = __builtin_amdgcn_mfma_f32_16x16x32_bf16(Bt[n][k], At[m][k], acc[ai][bj][m][n], 0, 0, 0); __builtin_amdgcn_s_setprio(0); } while (0)
; #define PG8_WAIT_V(n) asm volatile("s_waitcnt vmcnt(" #n ")" ::: "memory")
; #define PG8_WAIT_L(n) asm volatile("s_waitcnt lgkmcnt(" #n ")" ::: "memory")
; #define PG8_BAR __builtin_amdgcn_s_barrier()
; #define PG8_SCHED __builtin_amdgcn_sched_barrier(0)
; template <class EpiT, class Sched>
; __device__ __forceinline__ void gemm_phase(LAS unsigned char* lds, const Gemm g, const Sched& S, const EpiT& E, int wv) {
;     ...
;             PG8_LDB(B0, 1, 0); PG8_LDB(B1, 1, 1); PG8_SCHED; PG8_LDA(At, 1, 0); PG8_STAGE(PG8_SA(0, 1), a2 + hstepA, voffA);
;             PG8_WAIT_V(8); PG8_WAIT_L(0); PG8_BAR; PG8_MMA(0, 0, At, B0); PG8_MMA(0, 1, At, B1); PG8_BAR; PG8_SCHED;
;             PG8_LDA(At, 1, 1); PG8_STAGE(PG8_SB(1, 0), b3, voffB); PG8_STAGE(PG8_SB(1, 1), b3 + hstepB, voffB); PG8_STAGE(PG8_SA(1, 0), a3, voffA);
;             PG8_WAIT_V(8); PG8_WAIT_L(0); PG8_BAR; PG8_MMA(1, 0, At, B0); PG8_MMA(1, 1, At, B1); PG8_BAR; PG8_SCHED;
;         }
;         if (wr == 0) PG8_BAR;
	s_add_i32 s56, 0, 0x18000
	s_add_i32 s57, 0, 0x1c000
	ds_read_b128 v[128:131], v252
	ds_read_b128 v[132:135], v252 offset:1024
	ds_read_b128 v[146:149], v252 offset:2048
	ds_read_b128 v[150:153], v252 offset:3072
	ds_read_b128 v[154:157], v253
	ds_read_b128 v[160:163], v253 offset:1024
	ds_read_b128 v[164:167], v253 offset:2048
	ds_read_b128 v[168:171], v253 offset:3072
	s_add_u32 s26, s26, 0x40000
	s_addc_u32 s27, s27, 0
	s_mov_b32 m0, s38
	ds_read_b128 v[172:175], v159 offset:32768
	ds_read_b128 v[176:179], v159 offset:33792
	ds_read_b128 v[180:183], v159 offset:34816
	ds_read_b128 v[184:187], v159 offset:35840
	ds_read_b128 v[188:191], v159 offset:36864
	ds_read_b128 v[204:207], v159 offset:37888
	ds_read_b128 v[208:211], v159 offset:38912
	ds_read_b128 v[212:215], v159 offset:39936
	global_load_lds_dwordx4 v136, s[26:27]
	s_mov_b32 m0, s39
	s_nop 0
	global_load_lds_dwordx4 v138, s[26:27]
	s_waitcnt vmcnt(8)
	s_waitcnt lgkmcnt(0)
	s_barrier
	s_setprio 1
	v_mfma_f32_16x16x32_bf16 v[124:127], v[128:131], v[172:175], v[124:127]
	v_mfma_f32_16x16x32_bf16 v[120:123], v[146:149], v[172:175], v[120:123]
	v_mfma_f32_16x16x32_bf16 v[116:119], v[128:131], v[180:183], v[116:119]
	v_mfma_f32_16x16x32_bf16 v[112:115], v[146:149], v[180:183], v[112:115]
	v_mfma_f32_16x16x32_bf16 v[108:111], v[128:131], v[188:191], v[108:111]
	v_mfma_f32_16x16x32_bf16 v[104:107], v[146:149], v[188:191], v[104:107]
	v_mfma_f32_16x16x32_bf16 v[100:103], v[128:131], v[208:211], v[100:103]
	v_mfma_f32_16x16x32_bf16 v[96:99], v[146:149], v[208:211], v[96:99]
	v_mfma_f32_16x16x32_bf16 v[124:127], v[132:135], v[176:179], v[124:127]
	v_mfma_f32_16x16x32_bf16 v[120:123], v[150:153], v[176:179], v[120:123]
	v_mfma_f32_16x16x32_bf16 v[116:119], v[132:135], v[184:187], v[116:119]
	v_mfma_f32_16x16x32_bf16 v[112:115], v[150:153], v[184:187], v[112:115]
	v_mfma_f32_16x16x32_bf16 v[108:111], v[132:135], v[204:207], v[108:111]
	v_mfma_f32_16x16x32_bf16 v[104:107], v[150:153], v[204:207], v[104:107]
	v_mfma_f32_16x16x32_bf16 v[100:103], v[132:135], v[212:215], v[100:103]
	v_mfma_f32_16x16x32_bf16 v[96:99], v[150:153], v[212:215], v[96:99]
	v_mfma_f32_16x16x32_bf16 v[68:71], v[154:157], v[172:175], v[68:71]
	v_mfma_f32_16x16x32_bf16 v[64:67], v[164:167], v[172:175], v[64:67]
	v_mfma_f32_16x16x32_bf16 v[52:55], v[154:157], v[180:183], v[52:55]
	v_mfma_f32_16x16x32_bf16 v[48:51], v[164:167], v[180:183], v[48:51]
	v_mfma_f32_16x16x32_bf16 v[44:47], v[154:157], v[188:191], v[44:47]
	v_mfma_f32_16x16x32_bf16 v[40:43], v[164:167], v[188:191], v[40:43]
	v_mfma_f32_16x16x32_bf16 v[36:39], v[154:157], v[208:211], v[36:39]
	v_mfma_f32_16x16x32_bf16 v[32:35], v[164:167], v[208:211], v[32:35]
	v_mfma_f32_16x16x32_bf16 v[68:71], v[160:163], v[176:179], v[68:71]
	v_mfma_f32_16x16x32_bf16 v[64:67], v[168:171], v[176:179], v[64:67]
	v_mfma_f32_16x16x32_bf16 v[52:55], v[160:163], v[184:187], v[52:55]
	v_mfma_f32_16x16x32_bf16 v[48:51], v[168:171], v[184:187], v[48:51]
	v_mfma_f32_16x16x32_bf16 v[44:47], v[160:163], v[204:207], v[44:47]
	v_mfma_f32_16x16x32_bf16 v[40:43], v[168:171], v[204:207], v[40:43]
	v_mfma_f32_16x16x32_bf16 v[36:39], v[160:163], v[212:215], v[36:39]
	v_mfma_f32_16x16x32_bf16 v[32:35], v[168:171], v[212:215], v[32:35]
	s_setprio 0
	s_barrier
	s_add_i32 s26, s56, s33
	s_mov_b32 m0, s26
	ds_read_b128 v[172:175], v159 offset:49152
	ds_read_b128 v[176:179], v159 offset:50176
	ds_read_b128 v[180:183], v159 offset:51200
	ds_read_b128 v[184:187], v159 offset:52224
	ds_read_b128 v[188:191], v159 offset:53248
	ds_read_b128 v[204:207], v159 offset:54272
	ds_read_b128 v[208:211], v159 offset:55296
	ds_read_b128 v[212:215], v159 offset:56320
	global_load_lds_dwordx4 v192, s[62:63]
	s_add_i32 m0, s26, 0x2000
	s_add_u32 s24, s24, 0x40080
	s_addc_u32 s25, s25, 0
	s_add_i32 s26, s57, s33
	global_load_lds_dwordx4 v140, s[62:63]
	s_mov_b32 m0, s26
	s_nop 0
	global_load_lds_dwordx4 v192, s[24:25]
	s_add_i32 m0, s26, 0x2000
	s_nop 0
	global_load_lds_dwordx4 v140, s[24:25]
	s_mov_b32 m0, s40
	s_nop 0
	global_load_lds_dwordx4 v136, s[64:65]
	s_mov_b32 m0, s41
	s_nop 0
	global_load_lds_dwordx4 v138, s[64:65]
	s_waitcnt vmcnt(8)
	s_waitcnt lgkmcnt(0)
	s_barrier
	s_setprio 1
	v_mfma_f32_16x16x32_bf16 v[92:95], v[128:131], v[172:175], v[92:95]
	v_mfma_f32_16x16x32_bf16 v[88:91], v[146:149], v[172:175], v[88:91]
	v_mfma_f32_16x16x32_bf16 v[84:87], v[128:131], v[180:183], v[84:87]
	v_mfma_f32_16x16x32_bf16 v[80:83], v[146:149], v[180:183], v[80:83]
	v_mfma_f32_16x16x32_bf16 v[76:79], v[128:131], v[188:191], v[76:79]
	v_mfma_f32_16x16x32_bf16 v[72:75], v[146:149], v[188:191], v[72:75]
	v_mfma_f32_16x16x32_bf16 v[60:63], v[128:131], v[208:211], v[60:63]
	v_mfma_f32_16x16x32_bf16 v[56:59], v[146:149], v[208:211], v[56:59]
	v_mfma_f32_16x16x32_bf16 v[92:95], v[132:135], v[176:179], v[92:95]
	v_mfma_f32_16x16x32_bf16 v[88:91], v[150:153], v[176:179], v[88:91]
	v_mfma_f32_16x16x32_bf16 v[84:87], v[132:135], v[184:187], v[84:87]
	v_mfma_f32_16x16x32_bf16 v[80:83], v[150:153], v[184:187], v[80:83]
	v_mfma_f32_16x16x32_bf16 v[76:79], v[132:135], v[204:207], v[76:79]
	v_mfma_f32_16x16x32_bf16 v[72:75], v[150:153], v[204:207], v[72:75]
	v_mfma_f32_16x16x32_bf16 v[60:63], v[132:135], v[212:215], v[60:63]
	v_mfma_f32_16x16x32_bf16 v[56:59], v[150:153], v[212:215], v[56:59]
	v_mfma_f32_16x16x32_bf16 v[28:31], v[154:157], v[172:175], v[28:31]
	v_mfma_f32_16x16x32_bf16 v[24:27], v[164:167], v[172:175], v[24:27]
	v_mfma_f32_16x16x32_bf16 v[20:23], v[154:157], v[180:183], v[20:23]
	v_mfma_f32_16x16x32_bf16 v[16:19], v[164:167], v[180:183], v[16:19]
	v_mfma_f32_16x16x32_bf16 v[12:15], v[154:157], v[188:191], v[12:15]
	v_mfma_f32_16x16x32_bf16 v[8:11], v[164:167], v[188:191], v[8:11]
	v_mfma_f32_16x16x32_bf16 v[4:7], v[154:157], v[208:211], v[4:7]
	v_mfma_f32_16x16x32_bf16 v[0:3], v[164:167], v[208:211], v[0:3]
	v_mfma_f32_16x16x32_bf16 v[28:31], v[160:163], v[176:179], v[28:31]
	v_mfma_f32_16x16x32_bf16 v[24:27], v[168:171], v[176:179], v[24:27]
	v_mfma_f32_16x16x32_bf16 v[20:23], v[160:163], v[184:187], v[20:23]
	v_mfma_f32_16x16x32_bf16 v[16:19], v[168:171], v[184:187], v[16:19]
	v_mfma_f32_16x16x32_bf16 v[12:15], v[160:163], v[204:207], v[12:15]
	v_mfma_f32_16x16x32_bf16 v[8:11], v[168:171], v[204:207], v[8:11]
	v_mfma_f32_16x16x32_bf16 v[4:7], v[160:163], v[212:215], v[4:7]
	v_mfma_f32_16x16x32_bf16 v[0:3], v[168:171], v[212:215], v[0:3]
	s_setprio 0
	s_barrier
	s_add_i32 s55, s55, 2
	s_add_u32 s22, s22, 0x100
	s_addc_u32 s23, s23, 0
	s_add_u32 s53, s53, 0x100
	s_addc_u32 s54, s54, 0
	s_cmp_gt_u32 s55, 13
	s_cbranch_scc0 .LBB0_1271
	s_and_b64 vcc, exec, s[8:9]
	s_cbranch_vccz .LBB0_1274
	s_barrier

; #define PG8_STAGE(bufoff, gbase, voff) do { _Pragma("unroll") for (int _i = 0; _i < 2; ++_i) \
;         __builtin_amdgcn_global_load_lds((const unsigned*)((const char*)(gbase) + (voff)[_i]), (LAS unsigned*)(lds + (bufoff) + ldsw + _i * 8192), 16, 0, 0); } while (0)
; #define PG8_LDA(dst, b, h) do { _Pragma("unroll") for (int m = 0; m < 4; ++m) _Pragma("unroll") for (int k = 0; k < 2; ++k) dst[m][k] = *(const LAS bf16x8*)(lds + PG8_SA(b, h) + aoff + m * 2048 + k * 1024); } while (0)
; #define PG8_LDB(dst, b, h) do { _Pragma("unroll") for (int n = 0; n < 2; ++n) _Pragma("unroll") for (int k = 0; k < 2; ++k) dst[n][k] = *(const LAS bf16x8*)(lds + PG8_SB(b, h) + boff + n * 2048 + k * 1024); } while (0)
; #define PG8_MMA(ai, bj, At, Bt) do { __builtin_amdgcn_s_setprio(1); _Pragma("unroll") for (int m = 0; m < 4; ++m) _Pragma("unroll") for (int n = 0; n < 2; ++n) _Pragma("unroll") for (int k = 0; k < 2; ++k) \
;         acc[ai][bj][m][n] = __builtin_amdgcn_mfma_f32_16x16x32_bf16(Bt[n][k], At[m][k], acc[ai][bj][m][n], 0, 0, 0); __builtin_amdgcn_s_setprio(0); } while (0)
; #define PG8_WAIT_V(n) asm volatile("s_waitcnt vmcnt(" #n ")" ::: "memory")
; #define PG8_WAIT_L(n) asm volatile("s_waitcnt lgkmcnt(" #n ")" ::: "memory")
; #define PG8_BAR __builtin_amdgcn_s_barrier()
; #define PG8_SCHED __builtin_amdgcn_sched_barrier(0)
; template <class EpiT, class Sched>
; __device__ __forceinline__ void gemm_phase(LAS unsigned char* lds, const Gemm g, const Sched& S, const EpiT& E, int wv) {
;     ...
;             const bool last = (t == nt - 2);
;             const char* a1 = cA + (size_t)(t + 1) * kstep;
;             const char* a2 = last ? nA : cA + (size_t)(t + 2) * kstep; const char* b2 = last ? nB : cB + (size_t)(t + 2) * kstep;
;             const char* a3 = a2 + kstep; const char* b3 = b2 + kstep;
;             PG8_LDB(B0, 0, 0); PG8_LDB(B1, 0, 1); PG8_SCHED; PG8_LDA(At, 0, 0); PG8_STAGE(PG8_SA(1, 1), a1 + hstepA, voffA);
;             PG8_WAIT_V(8); PG8_WAIT_L(0); PG8_BAR; PG8_MMA(0, 0, At, B0); PG8_MMA(0, 1, At, B1); PG8_BAR; PG8_SCHED;
;             PG8_LDA(At, 0, 1); PG8_STAGE(PG8_SB(0, 0), b2, voffB); PG8_STAGE(PG8_SB(0, 1), b2 + hstepB, voffB); PG8_STAGE(PG8_SA(0, 0), a2, voffA);
;             PG8_WAIT_V(8); PG8_WAIT_L(0); PG8_BAR; PG8_MMA(1, 0, At, B0); PG8_MMA(1, 1, At, B1); PG8_BAR; PG8_SCHED;
.LBB0_1335:
	s_add_u32 s24, s4, 0xfff00080
	s_addc_u32 s25, s5, -1
	s_add_i32 s62, 0, 0x10000
	s_cmp_eq_u32 s59, 60
	s_cselect_b32 s27, s17, s25
	s_cselect_b32 s26, s19, s24
	s_cselect_b32 s25, s11, s58
	s_cselect_b32 s24, s23, s33
	s_add_i32 s64, 0, 0x14000
	ds_read_b128 v[128:131], v250
	ds_read_b128 v[132:135], v250 offset:1024
	ds_read_b128 v[136:139], v250 offset:2048
	ds_read_b128 v[140:143], v250 offset:3072
	ds_read_b128 v[144:147], v251
	ds_read_b128 v[148:151], v251 offset:1024
	ds_read_b128 v[152:155], v251 offset:2048
	ds_read_b128 v[156:159], v251 offset:3072
	s_add_i32 m0, s38, 0xc000
	ds_read_b128 v[160:163], v215
	ds_read_b128 v[164:167], v215 offset:1024
	ds_read_b128 v[178:181], v215 offset:2048
	ds_read_b128 v[182:185], v215 offset:3072
	ds_read_b128 v[186:189], v215 offset:4096
	ds_read_b128 v[204:207], v215 offset:5120
	ds_read_b128 v[208:211], v215 offset:6144
	ds_read_b128 v[216:219], v215 offset:7168
	global_load_lds_dwordx4 v174, s[4:5]
	s_add_i32 m0, s38, 0xe000
	s_nop 0
	global_load_lds_dwordx4 v176, s[4:5]
	s_waitcnt vmcnt(8)
	s_waitcnt lgkmcnt(0)
	s_barrier
	s_setprio 1
	v_mfma_f32_16x16x32_bf16 v[124:127], v[128:131], v[160:163], v[124:127]
	v_mfma_f32_16x16x32_bf16 v[120:123], v[136:139], v[160:163], v[120:123]
	v_mfma_f32_16x16x32_bf16 v[116:119], v[128:131], v[178:181], v[116:119]
	v_mfma_f32_16x16x32_bf16 v[112:115], v[136:139], v[178:181], v[112:115]
	v_mfma_f32_16x16x32_bf16 v[108:111], v[128:131], v[186:189], v[108:111]
	v_mfma_f32_16x16x32_bf16 v[104:107], v[136:139], v[186:189], v[104:107]
	v_mfma_f32_16x16x32_bf16 v[100:103], v[128:131], v[208:211], v[100:103]
	v_mfma_f32_16x16x32_bf16 v[96:99], v[136:139], v[208:211], v[96:99]
	v_mfma_f32_16x16x32_bf16 v[124:127], v[132:135], v[164:167], v[124:127]
	v_mfma_f32_16x16x32_bf16 v[120:123], v[140:143], v[164:167], v[120:123]
	v_mfma_f32_16x16x32_bf16 v[116:119], v[132:135], v[182:185], v[116:119]
	v_mfma_f32_16x16x32_bf16 v[112:115], v[140:143], v[182:185], v[112:115]
	v_mfma_f32_16x16x32_bf16 v[108:111], v[132:135], v[204:207], v[108:111]
	v_mfma_f32_16x16x32_bf16 v[104:107], v[140:143], v[204:207], v[104:107]
	v_mfma_f32_16x16x32_bf16 v[100:103], v[132:135], v[216:219], v[100:103]
	v_mfma_f32_16x16x32_bf16 v[96:99], v[140:143], v[216:219], v[96:99]
	v_mfma_f32_16x16x32_bf16 v[60:63], v[144:147], v[160:163], v[60:63]
	v_mfma_f32_16x16x32_bf16 v[56:59], v[152:155], v[160:163], v[56:59]
	v_mfma_f32_16x16x32_bf16 v[52:55], v[144:147], v[178:181], v[52:55]
	v_mfma_f32_16x16x32_bf16 v[48:51], v[152:155], v[178:181], v[48:51]
	v_mfma_f32_16x16x32_bf16 v[44:47], v[144:147], v[186:189], v[44:47]
	v_mfma_f32_16x16x32_bf16 v[40:43], v[152:155], v[186:189], v[40:43]
	v_mfma_f32_16x16x32_bf16 v[36:39], v[144:147], v[208:211], v[36:39]
	v_mfma_f32_16x16x32_bf16 v[32:35], v[152:155], v[208:211], v[32:35]
	v_mfma_f32_16x16x32_bf16 v[60:63], v[148:151], v[164:167], v[60:63]
	v_mfma_f32_16x16x32_bf16 v[56:59], v[156:159], v[164:167], v[56:59]
	v_mfma_f32_16x16x32_bf16 v[52:55], v[148:151], v[182:185], v[52:55]
	v_mfma_f32_16x16x32_bf16 v[48:51], v[156:159], v[182:185], v[48:51]
	v_mfma_f32_16x16x32_bf16 v[44:47], v[148:151], v[204:207], v[44:47]
	v_mfma_f32_16x16x32_bf16 v[40:43], v[156:159], v[204:207], v[40:43]
	v_mfma_f32_16x16x32_bf16 v[36:39], v[148:151], v[216:219], v[36:39]
	v_mfma_f32_16x16x32_bf16 v[32:35], v[156:159], v[216:219], v[32:35]
	s_setprio 0
	s_barrier
	s_add_i32 s62, s62, s37
	s_add_u32 s72, s24, s92
	s_addc_u32 s73, s25, s93
	s_mov_b32 m0, s62
	ds_read_b128 v[160:163], v215 offset:16384
	ds_read_b128 v[164:167], v215 offset:17408
	ds_read_b128 v[178:181], v215 offset:18432
	ds_read_b128 v[182:185], v215 offset:19456
	ds_read_b128 v[186:189], v215 offset:20480
	ds_read_b128 v[204:207], v215 offset:21504
	ds_read_b128 v[208:211], v215 offset:22528
	ds_read_b128 v[216:219], v215 offset:23552
	global_load_lds_dwordx4 v192, s[24:25]
	s_add_i32 m0, s62, 0x2000
	s_add_u32 s62, s24, 0x100000
	s_addc_u32 s63, s25, 0
	s_add_i32 s64, s64, s37
	global_load_lds_dwordx4 v172, s[24:25]
	s_mov_b32 m0, s64
	s_nop 0
	global_load_lds_dwordx4 v192, s[62:63]
	s_add_i32 m0, s64, 0x2000
	s_nop 0
	global_load_lds_dwordx4 v172, s[62:63]
	s_add_u32 s98, s26, s92
	s_addc_u32 s99, s27, s93
	s_mov_b32 m0, s38
	s_nop 0
	global_load_lds_dwordx4 v168, s[26:27]
	s_mov_b32 m0, s39
	s_nop 0
	global_load_lds_dwordx4 v170, s[26:27]
	s_waitcnt vmcnt(8)
	s_waitcnt lgkmcnt(0)
	s_barrier
	s_setprio 1
	v_mfma_f32_16x16x32_bf16 v[92:95], v[128:131], v[160:163], v[92:95]
	v_mfma_f32_16x16x32_bf16 v[88:91], v[136:139], v[160:163], v[88:91]
	v_mfma_f32_16x16x32_bf16 v[84:87], v[128:131], v[178:181], v[84:87]
	v_mfma_f32_16x16x32_bf16 v[80:83], v[136:139], v[178:181], v[80:83]
	v_mfma_f32_16x16x32_bf16 v[76:79], v[128:131], v[186:189], v[76:79]
	v_mfma_f32_16x16x32_bf16 v[72:75], v[136:139], v[186:189], v[72:75]
	v_mfma_f32_16x16x32_bf16 v[68:71], v[128:131], v[208:211], v[68:71]
	v_mfma_f32_16x16x32_bf16 v[64:67], v[136:139], v[208:211], v[64:67]
	v_mfma_f32_16x16x32_bf16 v[92:95], v[132:135], v[164:167], v[92:95]
	v_mfma_f32_16x16x32_bf16 v[88:91], v[140:143], v[164:167], v[88:91]
	v_mfma_f32_16x16x32_bf16 v[84:87], v[132:135], v[182:185], v[84:87]
	v_mfma_f32_16x16x32_bf16 v[80:83], v[140:143], v[182:185], v[80:83]
	v_mfma_f32_16x16x32_bf16 v[76:79], v[132:135], v[204:207], v[76:79]
	v_mfma_f32_16x16x32_bf16 v[72:75], v[140:143], v[204:207], v[72:75]
	v_mfma_f32_16x16x32_bf16 v[68:71], v[132:135], v[216:219], v[68:71]
	v_mfma_f32_16x16x32_bf16 v[64:67], v[140:143], v[216:219], v[64:67]
	v_mfma_f32_16x16x32_bf16 v[28:31], v[144:147], v[160:163], v[28:31]
	v_mfma_f32_16x16x32_bf16 v[24:27], v[152:155], v[160:163], v[24:27]
	v_mfma_f32_16x16x32_bf16 v[20:23], v[144:147], v[178:181], v[20:23]
	v_mfma_f32_16x16x32_bf16 v[16:19], v[152:155], v[178:181], v[16:19]
	v_mfma_f32_16x16x32_bf16 v[12:15], v[144:147], v[186:189], v[12:15]
	v_mfma_f32_16x16x32_bf16 v[8:11], v[152:155], v[186:189], v[8:11]
	v_mfma_f32_16x16x32_bf16 v[4:7], v[144:147], v[208:211], v[4:7]
	v_mfma_f32_16x16x32_bf16 v[0:3], v[152:155], v[208:211], v[0:3]
	v_mfma_f32_16x16x32_bf16 v[28:31], v[148:151], v[164:167], v[28:31]
	v_mfma_f32_16x16x32_bf16 v[24:27], v[156:159], v[164:167], v[24:27]
	v_mfma_f32_16x16x32_bf16 v[20:23], v[148:151], v[182:185], v[20:23]
	v_mfma_f32_16x16x32_bf16 v[16:19], v[156:159], v[182:185], v[16:19]
	v_mfma_f32_16x16x32_bf16 v[12:15], v[148:151], v[204:207], v[12:15]
	v_mfma_f32_16x16x32_bf16 v[8:11], v[156:159], v[204:207], v[8:11]
	v_mfma_f32_16x16x32_bf16 v[4:7], v[148:151], v[216:219], v[4:7]
	v_mfma_f32_16x16x32_bf16 v[0:3], v[156:159], v[216:219], v[0:3]
	s_setprio 0
	s_barrier
; #define PG8_STAGE(bufoff, gbase, voff) do { _Pragma("unroll") for (int _i = 0; _i < 2; ++_i) \
;         __builtin_amdgcn_global_load_lds((const unsigned*)((const char*)(gbase) + (voff)[_i]), (LAS unsigned*)(lds + (bufoff) + ldsw + _i * 8192), 16, 0, 0); } while (0)
; #define PG8_LDA(dst, b, h) do { _Pragma("unroll") for (int m = 0; m < 4; ++m) _Pragma("unroll") for (int k = 0; k < 2; ++k) dst[m][k] = *(const LAS bf16x8*)(lds + PG8_SA(b, h) + aoff + m * 2048 + k * 1024); } while (0)
; #define PG8_LDB(dst, b, h) do { _Pragma("unroll") for (int n = 0; n < 2; ++n) _Pragma("unroll") for (int k = 0; k < 2; ++k) dst[n][k] = *(const LAS bf16x8*)(lds + PG8_SB(b, h) + boff + n * 2048 + k * 1024); } while (0)
; #define PG8_MMA(ai, bj, At, Bt) do { __builtin_amdgcn_s_setprio(1); _Pragma("unroll") for (int m = 0; m < 4; ++m) _Pragma("unroll") for (int n = 0; n < 2; ++n) _Pragma("unroll") for (int k = 0; k < 2; ++k) \
;         acc[ai][bj][m][n] = __builtin_amdgcn_mfma_f32_16x16x32_bf16(Bt[n][k], At[m][k], acc[ai][bj][m][n], 0, 0, 0); __builtin_amdgcn_s_setprio(0); } while (0)
; #define PG8_WAIT_V(n) asm volatile("s_waitcnt vmcnt(" #n ")" ::: "memory")
; #define PG8_WAIT_L(n) asm volatile("s_waitcnt lgkmcnt(" #n ")" ::: "memory")
; #define PG8_BAR __builtin_amdgcn_s_barrier()
; #define PG8_SCHED __builtin_amdgcn_sched_barrier(0)
; template <class EpiT, class Sched>
; __device__ __forceinline__ void gemm_phase(LAS unsigned char* lds, const Gemm g, const Sched& S, const EpiT& E, int wv) {
;     ...
;             PG8_LDB(B0, 1, 0); PG8_LDB(B1, 1, 1); PG8_SCHED; PG8_LDA(At, 1, 0); PG8_STAGE(PG8_SA(0, 1), a2 + hstepA, voffA);
;             PG8_WAIT_V(8); PG8_WAIT_L(0); PG8_BAR; PG8_MMA(0, 0, At, B0); PG8_MMA(0, 1, At, B1); PG8_BAR; PG8_SCHED;
;             PG8_LDA(At, 1, 1); PG8_STAGE(PG8_SB(1, 0), b3, voffB); PG8_STAGE(PG8_SB(1, 1), b3 + hstepB, voffB); PG8_STAGE(PG8_SA(1, 0), a3, voffA);
;             PG8_WAIT_V(8); PG8_WAIT_L(0); PG8_BAR; PG8_MMA(1, 0, At, B0); PG8_MMA(1, 1, At, B1); PG8_BAR; PG8_SCHED;
;         }
;         if (wr == 0) PG8_BAR;
	s_add_i32 s62, 0, 0x18000
	s_add_i32 s63, 0, 0x1c000
	ds_read_b128 v[128:131], v252
	ds_read_b128 v[132:135], v252 offset:1024
	ds_read_b128 v[136:139], v252 offset:2048
	ds_read_b128 v[140:143], v252 offset:3072
	ds_read_b128 v[144:147], v253
	ds_read_b128 v[148:151], v253 offset:1024
	ds_read_b128 v[152:155], v253 offset:2048
	ds_read_b128 v[156:159], v253 offset:3072
	s_add_u32 s26, s26, 0x100000
	s_addc_u32 s27, s27, 0
	s_mov_b32 m0, s40
	ds_read_b128 v[160:163], v215 offset:32768
	ds_read_b128 v[164:167], v215 offset:33792
	ds_read_b128 v[178:181], v215 offset:34816
	ds_read_b128 v[182:185], v215 offset:35840
	ds_read_b128 v[186:189], v215 offset:36864
	ds_read_b128 v[204:207], v215 offset:37888
	ds_read_b128 v[208:211], v215 offset:38912
	ds_read_b128 v[216:219], v215 offset:39936
	global_load_lds_dwordx4 v168, s[26:27]
	s_mov_b32 m0, s41
	s_nop 0
	global_load_lds_dwordx4 v170, s[26:27]
	s_waitcnt vmcnt(8)
	s_waitcnt lgkmcnt(0)
	s_barrier
	s_setprio 1
	v_mfma_f32_16x16x32_bf16 v[124:127], v[128:131], v[160:163], v[124:127]
	v_mfma_f32_16x16x32_bf16 v[120:123], v[136:139], v[160:163], v[120:123]
	v_mfma_f32_16x16x32_bf16 v[116:119], v[128:131], v[178:181], v[116:119]
	v_mfma_f32_16x16x32_bf16 v[112:115], v[136:139], v[178:181], v[112:115]
	v_mfma_f32_16x16x32_bf16 v[108:111], v[128:131], v[186:189], v[108:111]
	v_mfma_f32_16x16x32_bf16 v[104:107], v[136:139], v[186:189], v[104:107]
	v_mfma_f32_16x16x32_bf16 v[100:103], v[128:131], v[208:211], v[100:103]
	v_mfma_f32_16x16x32_bf16 v[96:99], v[136:139], v[208:211], v[96:99]
	v_mfma_f32_16x16x32_bf16 v[124:127], v[132:135], v[164:167], v[124:127]
	v_mfma_f32_16x16x32_bf16 v[120:123], v[140:143], v[164:167], v[120:123]
	v_mfma_f32_16x16x32_bf16 v[116:119], v[132:135], v[182:185], v[116:119]
	v_mfma_f32_16x16x32_bf16 v[112:115], v[140:143], v[182:185], v[112:115]
	v_mfma_f32_16x16x32_bf16 v[108:111], v[132:135], v[204:207], v[108:111]
	v_mfma_f32_16x16x32_bf16 v[104:107], v[140:143], v[204:207], v[104:107]
	v_mfma_f32_16x16x32_bf16 v[100:103], v[132:135], v[216:219], v[100:103]
	v_mfma_f32_16x16x32_bf16 v[96:99], v[140:143], v[216:219], v[96:99]
	v_mfma_f32_16x16x32_bf16 v[60:63], v[144:147], v[160:163], v[60:63]
	v_mfma_f32_16x16x32_bf16 v[56:59], v[152:155], v[160:163], v[56:59]
	v_mfma_f32_16x16x32_bf16 v[52:55], v[144:147], v[178:181], v[52:55]
	v_mfma_f32_16x16x32_bf16 v[48:51], v[152:155], v[178:181], v[48:51]
	v_mfma_f32_16x16x32_bf16 v[44:47], v[144:147], v[186:189], v[44:47]
	v_mfma_f32_16x16x32_bf16 v[40:43], v[152:155], v[186:189], v[40:43]
	v_mfma_f32_16x16x32_bf16 v[36:39], v[144:147], v[208:211], v[36:39]
	v_mfma_f32_16x16x32_bf16 v[32:35], v[152:155], v[208:211], v[32:35]
	v_mfma_f32_16x16x32_bf16 v[60:63], v[148:151], v[164:167], v[60:63]
	v_mfma_f32_16x16x32_bf16 v[56:59], v[156:159], v[164:167], v[56:59]
	v_mfma_f32_16x16x32_bf16 v[52:55], v[148:151], v[182:185], v[52:55]
	v_mfma_f32_16x16x32_bf16 v[48:51], v[156:159], v[182:185], v[48:51]
	v_mfma_f32_16x16x32_bf16 v[44:47], v[148:151], v[204:207], v[44:47]
	v_mfma_f32_16x16x32_bf16 v[40:43], v[156:159], v[204:207], v[40:43]
	v_mfma_f32_16x16x32_bf16 v[36:39], v[148:151], v[216:219], v[36:39]
	v_mfma_f32_16x16x32_bf16 v[32:35], v[156:159], v[216:219], v[32:35]
	s_setprio 0
	s_barrier
	s_add_i32 s26, s62, s37
	s_mov_b32 m0, s26
	ds_read_b128 v[160:163], v215 offset:49152
	ds_read_b128 v[164:167], v215 offset:50176
	ds_read_b128 v[178:181], v215 offset:51200
	ds_read_b128 v[182:185], v215 offset:52224
	ds_read_b128 v[186:189], v215 offset:53248
	ds_read_b128 v[204:207], v215 offset:54272
	ds_read_b128 v[208:211], v215 offset:55296
	ds_read_b128 v[216:219], v215 offset:56320
	global_load_lds_dwordx4 v192, s[72:73]
	s_add_i32 m0, s26, 0x2000
	s_add_u32 s24, s24, 0x100080
	s_addc_u32 s25, s25, 0
	s_add_i32 s26, s63, s37
	global_load_lds_dwordx4 v172, s[72:73]
	s_mov_b32 m0, s26
	s_nop 0
	global_load_lds_dwordx4 v192, s[24:25]
	s_add_i32 m0, s26, 0x2000
	s_nop 0
	global_load_lds_dwordx4 v172, s[24:25]
	s_mov_b32 m0, s50
	s_nop 0
	global_load_lds_dwordx4 v168, s[98:99]
	s_mov_b32 m0, s51
	s_nop 0
	global_load_lds_dwordx4 v170, s[98:99]
	s_waitcnt vmcnt(8)
	s_waitcnt lgkmcnt(0)
	s_barrier
	s_setprio 1
	v_mfma_f32_16x16x32_bf16 v[92:95], v[128:131], v[160:163], v[92:95]
	v_mfma_f32_16x16x32_bf16 v[88:91], v[136:139], v[160:163], v[88:91]
	v_mfma_f32_16x16x32_bf16 v[84:87], v[128:131], v[178:181], v[84:87]
	v_mfma_f32_16x16x32_bf16 v[80:83], v[136:139], v[178:181], v[80:83]
	v_mfma_f32_16x16x32_bf16 v[76:79], v[128:131], v[186:189], v[76:79]
	v_mfma_f32_16x16x32_bf16 v[72:75], v[136:139], v[186:189], v[72:75]
	v_mfma_f32_16x16x32_bf16 v[68:71], v[128:131], v[208:211], v[68:71]
	v_mfma_f32_16x16x32_bf16 v[64:67], v[136:139], v[208:211], v[64:67]
	v_mfma_f32_16x16x32_bf16 v[92:95], v[132:135], v[164:167], v[92:95]
	v_mfma_f32_16x16x32_bf16 v[88:91], v[140:143], v[164:167], v[88:91]
	v_mfma_f32_16x16x32_bf16 v[84:87], v[132:135], v[182:185], v[84:87]
	v_mfma_f32_16x16x32_bf16 v[80:83], v[140:143], v[182:185], v[80:83]
	v_mfma_f32_16x16x32_bf16 v[76:79], v[132:135], v[204:207], v[76:79]
	v_mfma_f32_16x16x32_bf16 v[72:75], v[140:143], v[204:207], v[72:75]
	v_mfma_f32_16x16x32_bf16 v[68:71], v[132:135], v[216:219], v[68:71]
	v_mfma_f32_16x16x32_bf16 v[64:67], v[140:143], v[216:219], v[64:67]
	v_mfma_f32_16x16x32_bf16 v[28:31], v[144:147], v[160:163], v[28:31]
	v_mfma_f32_16x16x32_bf16 v[24:27], v[152:155], v[160:163], v[24:27]
	v_mfma_f32_16x16x32_bf16 v[20:23], v[144:147], v[178:181], v[20:23]
	v_mfma_f32_16x16x32_bf16 v[16:19], v[152:155], v[178:181], v[16:19]
	v_mfma_f32_16x16x32_bf16 v[12:15], v[144:147], v[186:189], v[12:15]
	v_mfma_f32_16x16x32_bf16 v[8:11], v[152:155], v[186:189], v[8:11]
	v_mfma_f32_16x16x32_bf16 v[4:7], v[144:147], v[208:211], v[4:7]
	v_mfma_f32_16x16x32_bf16 v[0:3], v[152:155], v[208:211], v[0:3]
	v_mfma_f32_16x16x32_bf16 v[28:31], v[148:151], v[164:167], v[28:31]
	v_mfma_f32_16x16x32_bf16 v[24:27], v[156:159], v[164:167], v[24:27]
	v_mfma_f32_16x16x32_bf16 v[20:23], v[148:151], v[182:185], v[20:23]
	v_mfma_f32_16x16x32_bf16 v[16:19], v[156:159], v[182:185], v[16:19]
	v_mfma_f32_16x16x32_bf16 v[12:15], v[148:151], v[204:207], v[12:15]
	v_mfma_f32_16x16x32_bf16 v[8:11], v[156:159], v[204:207], v[8:11]
	v_mfma_f32_16x16x32_bf16 v[4:7], v[148:151], v[216:219], v[4:7]
	v_mfma_f32_16x16x32_bf16 v[0:3], v[156:159], v[216:219], v[0:3]
	s_setprio 0
	s_barrier
	s_add_i32 s59, s59, 2
	s_add_u32 s4, s4, 0x100
	s_addc_u32 s5, s5, 0
	s_add_u32 s33, s33, 0x100
	s_addc_u32 s58, s58, 0
	s_cmp_gt_u32 s59, 61
	s_cbranch_scc0 .LBB0_1335
	s_and_b64 vcc, exec, s[14:15]
	s_cbranch_vccz .LBB0_1338
	s_barrier
